# in-projection epilogue fully hand-written (adds the shared rope-key columns); hipcc epilogue no longer reached
# speedup vs baseline: 1.0308x; 1.0118x over previous
; #define G_STAGE(bufoff, gbase, voff) do { _Pragma("unroll") for (int _i = 0; _i < 2; ++_i) \
;         __builtin_amdgcn_global_load_lds((const unsigned*)((const char*)(gbase) + (voff)[_i]), (LAS unsigned*)(lds + (bufoff) + ldsw + _i * 8192), 16, 0, 0); } while (0)
; #define G_LDA(dst, b, h) do { _Pragma("unroll") for (int m = 0; m < 4; ++m) _Pragma("unroll") for (int k = 0; k < 2; ++k) dst[m][k] = *(const LAS bf16x8*)(lds + G_SA(b, h) + aoff + m * 2048 + k * 1024); } while (0)
; #define G_LDB(dst, b, h) do { _Pragma("unroll") for (int n = 0; n < 2; ++n) _Pragma("unroll") for (int k = 0; k < 2; ++k) dst[n][k] = *(const LAS bf16x8*)(lds + G_SB(b, h) + boff + n * 2048 + k * 1024); } while (0)
; #define G_MMA(ai, bj, At, Bt_) do { __builtin_amdgcn_s_setprio(1); _Pragma("unroll") for (int m = 0; m < 4; ++m) _Pragma("unroll") for (int n = 0; n < 2; ++n) _Pragma("unroll") for (int k = 0; k < 2; ++k) \
;         acc[ai][bj][m][n] = __builtin_amdgcn_mfma_f32_16x16x32_bf16(Bt_[n][k], At[m][k], acc[ai][bj][m][n], 0, 0, 0); __builtin_amdgcn_s_setprio(0); } while (0)
; #define G_WAIT_V(n) asm volatile("s_waitcnt vmcnt(" #n ")" ::: "memory")
; #define G_WAIT_L(n) asm volatile("s_waitcnt lgkmcnt(" #n ")" ::: "memory")
; #define G_BAR __builtin_amdgcn_s_barrier()
; #define G_SCHED __builtin_amdgcn_sched_barrier(0)
; template <class Epi, bool PERMROWS = false>
; DI void gemm_phase(LAS unsigned char* lds, const bf16_t* A, int lda, const bf16_t* Bt, int K, const Sched& S, const Epi& E) {
;     ...
;             G_LDB(B0, 0, 0); G_SCHED; G_LDA(At, 0, 0); G_STAGE(G_SA(1, 1), a1 + hstepA, voffA);
;             G_WAIT_L(8); G_BAR; G_WAIT_L(0); G_MMA(0, 0, At, B0); G_BAR; G_SCHED;
;             G_LDB(B1, 0, 1); G_STAGE(G_SB(0, 0), b2, voffB);
;             G_BAR; G_WAIT_L(0); G_MMA(0, 1, At, B1); G_BAR;
;             G_LDA(At, 0, 1); G_STAGE(G_SA(0, 0), a2, voffA);
;             G_BAR; G_WAIT_L(0); G_MMA(1, 0, At, B0); G_BAR; G_SCHED;
;             G_STAGE(G_SB(0, 1), b2 + hstepB, voffB);
;             G_WAIT_V(6); G_BAR; G_MMA(1, 1, At, B1); G_BAR;
.LBB0_534:
	s_waitcnt lgkmcnt(0)
	ds_read_b128 v[150:153], v174
	ds_read_b128 v[154:157], v174 offset:1024
	ds_read_b128 v[158:161], v174 offset:2048
	ds_read_b128 v[162:165], v174 offset:3072
	s_add_u32 s12, s10, 0xfff80080
	s_addc_u32 s13, s11, -1
	s_cmp_eq_u32 s62, 28
	s_cselect_b32 s57, s2, s13
	s_cselect_b32 s56, s3, s12
	s_cselect_b32 s13, s9, s37
	s_cselect_b32 s12, s27, s35
	v_lshl_add_u64 v[208:209], s[10:11], 0, v[144:145]
	s_add_i32 m0, s71, 0xc000
	ds_read_b128 v[166:169], v175
	ds_read_b128 v[178:181], v175 offset:1024
	ds_read_b128 v[182:185], v175 offset:2048
	ds_read_b128 v[186:189], v175 offset:3072
	ds_read_b128 v[190:193], v175 offset:4096
	ds_read_b128 v[194:197], v175 offset:5120
	ds_read_b128 v[198:201], v175 offset:6144
	ds_read_b128 v[204:207], v175 offset:7168
	global_load_lds_dwordx4 v[208:209], off
	v_lshl_add_u64 v[208:209], s[10:11], 0, v[142:143]
	s_add_i32 m0, s71, 0xe000
	s_nop 0
	global_load_lds_dwordx4 v[208:209], off
	s_waitcnt lgkmcnt(8)
	s_barrier
	s_waitcnt lgkmcnt(0)
	s_setprio 1
	s_waitcnt lgkmcnt(0)
	v_mfma_f32_16x16x32_bf16 v[124:127], v[150:153], v[166:169], v[124:127]
	v_mfma_f32_16x16x32_bf16 v[120:123], v[158:161], v[166:169], v[120:123]
	v_mfma_f32_16x16x32_bf16 v[108:111], v[150:153], v[182:185], v[108:111]
	v_mfma_f32_16x16x32_bf16 v[104:107], v[158:161], v[182:185], v[104:107]
	v_mfma_f32_16x16x32_bf16 v[92:95], v[150:153], v[190:193], v[92:95]
	v_mfma_f32_16x16x32_bf16 v[88:91], v[158:161], v[190:193], v[88:91]
	v_mfma_f32_16x16x32_bf16 v[76:79], v[150:153], v[198:201], v[76:79]
	v_mfma_f32_16x16x32_bf16 v[72:75], v[158:161], v[198:201], v[72:75]
	v_mfma_f32_16x16x32_bf16 v[124:127], v[154:157], v[178:181], v[124:127]
	v_mfma_f32_16x16x32_bf16 v[120:123], v[162:165], v[178:181], v[120:123]
	v_mfma_f32_16x16x32_bf16 v[108:111], v[154:157], v[186:189], v[108:111]
	v_mfma_f32_16x16x32_bf16 v[104:107], v[162:165], v[186:189], v[104:107]
	v_mfma_f32_16x16x32_bf16 v[92:95], v[154:157], v[194:197], v[92:95]
	v_mfma_f32_16x16x32_bf16 v[88:91], v[162:165], v[194:197], v[88:91]
	v_mfma_f32_16x16x32_bf16 v[76:79], v[154:157], v[204:207], v[76:79]
	v_mfma_f32_16x16x32_bf16 v[72:75], v[162:165], v[204:207], v[72:75]
	s_setprio 0
	s_barrier
	s_add_i32 s28, s85, s70
	v_lshl_add_u64 v[224:225], s[12:13], 0, v[128:129]
	s_mov_b32 m0, s28
	ds_read_b128 v[208:211], v176
	ds_read_b128 v[212:215], v176 offset:1024
	ds_read_b128 v[216:219], v176 offset:2048
	ds_read_b128 v[220:223], v176 offset:3072
	global_load_lds_dwordx4 v[224:225], off
	v_lshl_add_u64 v[226:227], s[12:13], 0, v[130:131]
	s_add_i32 m0, s28, 0x2000
	s_nop 0
	global_load_lds_dwordx4 v[226:227], off
	s_barrier
	s_waitcnt lgkmcnt(0)
	s_setprio 1
	s_waitcnt lgkmcnt(0)
	v_mfma_f32_16x16x32_bf16 v[116:119], v[208:211], v[166:169], v[116:119]
	v_mfma_f32_16x16x32_bf16 v[112:115], v[216:219], v[166:169], v[112:115]
	v_mfma_f32_16x16x32_bf16 v[100:103], v[208:211], v[182:185], v[100:103]
	v_mfma_f32_16x16x32_bf16 v[96:99], v[216:219], v[182:185], v[96:99]
	v_mfma_f32_16x16x32_bf16 v[84:87], v[208:211], v[190:193], v[84:87]
	v_mfma_f32_16x16x32_bf16 v[80:83], v[216:219], v[190:193], v[80:83]
	v_mfma_f32_16x16x32_bf16 v[68:71], v[208:211], v[198:201], v[68:71]
	v_mfma_f32_16x16x32_bf16 v[64:67], v[216:219], v[198:201], v[64:67]
	v_mfma_f32_16x16x32_bf16 v[116:119], v[212:215], v[178:181], v[116:119]
	v_mfma_f32_16x16x32_bf16 v[112:115], v[220:223], v[178:181], v[112:115]
	v_mfma_f32_16x16x32_bf16 v[100:103], v[212:215], v[186:189], v[100:103]
	v_mfma_f32_16x16x32_bf16 v[96:99], v[220:223], v[186:189], v[96:99]
	v_mfma_f32_16x16x32_bf16 v[84:87], v[212:215], v[194:197], v[84:87]
	v_mfma_f32_16x16x32_bf16 v[80:83], v[220:223], v[194:197], v[80:83]
	v_mfma_f32_16x16x32_bf16 v[68:71], v[212:215], v[204:207], v[68:71]
	v_mfma_f32_16x16x32_bf16 v[64:67], v[220:223], v[204:207], v[64:67]
	s_setprio 0
	s_mov_b32 m0, s71
	v_lshl_add_u64 v[228:229], s[56:57], 0, v[128:129]
	s_barrier
	ds_read_b128 v[166:169], v175 offset:16384
	ds_read_b128 v[178:181], v175 offset:17408
	ds_read_b128 v[182:185], v175 offset:18432
	ds_read_b128 v[186:189], v175 offset:19456
	ds_read_b128 v[190:193], v175 offset:20480
	ds_read_b128 v[194:197], v175 offset:21504
	ds_read_b128 v[198:201], v175 offset:22528
	ds_read_b128 v[204:207], v175 offset:23552
	global_load_lds_dwordx4 v[228:229], off
	v_lshl_add_u64 v[230:231], s[56:57], 0, v[130:131]
	s_mov_b32 m0, s72
	s_nop 0
	global_load_lds_dwordx4 v[230:231], off
	s_barrier
	s_waitcnt lgkmcnt(0)
	s_setprio 1
	s_waitcnt lgkmcnt(0)
	v_mfma_f32_16x16x32_bf16 v[60:63], v[150:153], v[166:169], v[60:63]
	v_mfma_f32_16x16x32_bf16 v[56:59], v[158:161], v[166:169], v[56:59]
	v_mfma_f32_16x16x32_bf16 v[44:47], v[150:153], v[182:185], v[44:47]
	v_mfma_f32_16x16x32_bf16 v[40:43], v[158:161], v[182:185], v[40:43]
	v_mfma_f32_16x16x32_bf16 v[28:31], v[150:153], v[190:193], v[28:31]
	v_mfma_f32_16x16x32_bf16 v[24:27], v[158:161], v[190:193], v[24:27]
	v_mfma_f32_16x16x32_bf16 v[12:15], v[150:153], v[198:201], v[12:15]
	v_mfma_f32_16x16x32_bf16 v[8:11], v[158:161], v[198:201], v[8:11]
	v_mfma_f32_16x16x32_bf16 v[60:63], v[154:157], v[178:181], v[60:63]
	v_mfma_f32_16x16x32_bf16 v[56:59], v[162:165], v[178:181], v[56:59]
	v_mfma_f32_16x16x32_bf16 v[44:47], v[154:157], v[186:189], v[44:47]
	v_mfma_f32_16x16x32_bf16 v[40:43], v[162:165], v[186:189], v[40:43]
	v_mfma_f32_16x16x32_bf16 v[28:31], v[154:157], v[194:197], v[28:31]
	v_mfma_f32_16x16x32_bf16 v[24:27], v[162:165], v[194:197], v[24:27]
	v_mfma_f32_16x16x32_bf16 v[12:15], v[154:157], v[204:207], v[12:15]
	v_mfma_f32_16x16x32_bf16 v[8:11], v[162:165], v[204:207], v[8:11]
	s_setprio 0
	s_barrier
; #define G_STAGE(bufoff, gbase, voff) do { _Pragma("unroll") for (int _i = 0; _i < 2; ++_i) \
;         __builtin_amdgcn_global_load_lds((const unsigned*)((const char*)(gbase) + (voff)[_i]), (LAS unsigned*)(lds + (bufoff) + ldsw + _i * 8192), 16, 0, 0); } while (0)
; #define G_LDA(dst, b, h) do { _Pragma("unroll") for (int m = 0; m < 4; ++m) _Pragma("unroll") for (int k = 0; k < 2; ++k) dst[m][k] = *(const LAS bf16x8*)(lds + G_SA(b, h) + aoff + m * 2048 + k * 1024); } while (0)
; #define G_LDB(dst, b, h) do { _Pragma("unroll") for (int n = 0; n < 2; ++n) _Pragma("unroll") for (int k = 0; k < 2; ++k) dst[n][k] = *(const LAS bf16x8*)(lds + G_SB(b, h) + boff + n * 2048 + k * 1024); } while (0)
; #define G_MMA(ai, bj, At, Bt_) do { __builtin_amdgcn_s_setprio(1); _Pragma("unroll") for (int m = 0; m < 4; ++m) _Pragma("unroll") for (int n = 0; n < 2; ++n) _Pragma("unroll") for (int k = 0; k < 2; ++k) \
;         acc[ai][bj][m][n] = __builtin_amdgcn_mfma_f32_16x16x32_bf16(Bt_[n][k], At[m][k], acc[ai][bj][m][n], 0, 0, 0); __builtin_amdgcn_s_setprio(0); } while (0)
; #define G_WAIT_V(n) asm volatile("s_waitcnt vmcnt(" #n ")" ::: "memory")
; #define G_WAIT_L(n) asm volatile("s_waitcnt lgkmcnt(" #n ")" ::: "memory")
; #define G_BAR __builtin_amdgcn_s_barrier()
; #define G_SCHED __builtin_amdgcn_sched_barrier(0)
; template <class Epi, bool PERMROWS = false>
; DI void gemm_phase(LAS unsigned char* lds, const bf16_t* A, int lda, const bf16_t* Bt, int K, const Sched& S, const Epi& E) {
;     ...
;             G_WAIT_V(6); G_BAR; G_MMA(1, 1, At, B1); G_BAR;
;             G_LDB(B0, 1, 0); G_SCHED; G_LDA(At, 1, 0); G_STAGE(G_SA(0, 1), a2 + hstepA, voffA);
;             G_WAIT_L(8); G_BAR; G_WAIT_L(0); G_MMA(0, 0, At, B0); G_BAR; G_SCHED;
;             G_LDB(B1, 1, 1); G_STAGE(G_SB(1, 0), b3, voffB);
;             G_BAR; G_WAIT_L(0); G_MMA(0, 1, At, B1); G_BAR;
;             G_LDA(At, 1, 1); G_STAGE(G_SA(1, 0), a3, voffA);
;             G_BAR; G_WAIT_L(0); G_MMA(1, 0, At, B0); G_BAR; G_SCHED;
	s_add_u32 s28, s12, 0x80000
	s_addc_u32 s29, s13, 0
	s_add_i32 s63, s86, s70
	v_lshl_add_u64 v[150:151], s[28:29], 0, v[128:129]
	s_mov_b32 m0, s63
	s_nop 0
	global_load_lds_dwordx4 v[150:151], off
	v_lshl_add_u64 v[150:151], s[28:29], 0, v[130:131]
	s_add_i32 m0, s63, 0x2000
	s_nop 0
	global_load_lds_dwordx4 v[150:151], off
	s_waitcnt vmcnt(6)
	s_barrier
	s_setprio 1
	v_mfma_f32_16x16x32_bf16 v[52:55], v[208:211], v[166:169], v[52:55]
	v_mfma_f32_16x16x32_bf16 v[48:51], v[216:219], v[166:169], v[48:51]
	v_mfma_f32_16x16x32_bf16 v[36:39], v[208:211], v[182:185], v[36:39]
	v_mfma_f32_16x16x32_bf16 v[32:35], v[216:219], v[182:185], v[32:35]
	v_mfma_f32_16x16x32_bf16 v[20:23], v[208:211], v[190:193], v[20:23]
	v_mfma_f32_16x16x32_bf16 v[16:19], v[216:219], v[190:193], v[16:19]
	v_mfma_f32_16x16x32_bf16 v[4:7], v[208:211], v[198:201], v[4:7]
	v_mfma_f32_16x16x32_bf16 v[0:3], v[216:219], v[198:201], v[0:3]
	v_mfma_f32_16x16x32_bf16 v[52:55], v[212:215], v[178:181], v[52:55]
	v_mfma_f32_16x16x32_bf16 v[48:51], v[220:223], v[178:181], v[48:51]
	v_mfma_f32_16x16x32_bf16 v[36:39], v[212:215], v[186:189], v[36:39]
	v_mfma_f32_16x16x32_bf16 v[32:35], v[220:223], v[186:189], v[32:35]
	v_mfma_f32_16x16x32_bf16 v[20:23], v[212:215], v[194:197], v[20:23]
	v_mfma_f32_16x16x32_bf16 v[16:19], v[220:223], v[194:197], v[16:19]
	v_mfma_f32_16x16x32_bf16 v[4:7], v[212:215], v[204:207], v[4:7]
	v_mfma_f32_16x16x32_bf16 v[0:3], v[220:223], v[204:207], v[0:3]
	s_setprio 0
	s_add_i32 s63, 0, 0x18000
	v_add_u32_e32 v132, s63, v170
	s_barrier
	ds_read_b128 v[150:153], v132
	ds_read_b128 v[154:157], v132 offset:1024
	ds_read_b128 v[158:161], v132 offset:2048
	ds_read_b128 v[162:165], v132 offset:3072
	s_add_u32 s28, s56, 0x80000
	s_addc_u32 s29, s57, 0
	s_mov_b32 m0, s73
	v_lshl_add_u64 v[208:209], s[28:29], 0, v[128:129]
	ds_read_b128 v[166:169], v175 offset:32768
	ds_read_b128 v[178:181], v175 offset:33792
	ds_read_b128 v[182:185], v175 offset:34816
	ds_read_b128 v[186:189], v175 offset:35840
	ds_read_b128 v[190:193], v175 offset:36864
	ds_read_b128 v[194:197], v175 offset:37888
	ds_read_b128 v[198:201], v175 offset:38912
	ds_read_b128 v[204:207], v175 offset:39936
	global_load_lds_dwordx4 v[208:209], off
	v_lshl_add_u64 v[208:209], s[28:29], 0, v[130:131]
	s_mov_b32 m0, s74
	s_nop 0
	global_load_lds_dwordx4 v[208:209], off
	s_waitcnt lgkmcnt(8)
	s_barrier
	s_waitcnt lgkmcnt(0)
	s_setprio 1
	s_waitcnt lgkmcnt(0)
	v_mfma_f32_16x16x32_bf16 v[124:127], v[150:153], v[166:169], v[124:127]
	v_mfma_f32_16x16x32_bf16 v[120:123], v[158:161], v[166:169], v[120:123]
	v_mfma_f32_16x16x32_bf16 v[108:111], v[150:153], v[182:185], v[108:111]
	v_mfma_f32_16x16x32_bf16 v[104:107], v[158:161], v[182:185], v[104:107]
	v_mfma_f32_16x16x32_bf16 v[92:95], v[150:153], v[190:193], v[92:95]
	v_mfma_f32_16x16x32_bf16 v[88:91], v[158:161], v[190:193], v[88:91]
	v_mfma_f32_16x16x32_bf16 v[76:79], v[150:153], v[198:201], v[76:79]
	v_mfma_f32_16x16x32_bf16 v[72:75], v[158:161], v[198:201], v[72:75]
	v_mfma_f32_16x16x32_bf16 v[124:127], v[154:157], v[178:181], v[124:127]
	v_mfma_f32_16x16x32_bf16 v[120:123], v[162:165], v[178:181], v[120:123]
	v_mfma_f32_16x16x32_bf16 v[108:111], v[154:157], v[186:189], v[108:111]
	v_mfma_f32_16x16x32_bf16 v[104:107], v[162:165], v[186:189], v[104:107]
	v_mfma_f32_16x16x32_bf16 v[92:95], v[154:157], v[194:197], v[92:95]
	v_mfma_f32_16x16x32_bf16 v[88:91], v[162:165], v[194:197], v[88:91]
	v_mfma_f32_16x16x32_bf16 v[76:79], v[154:157], v[204:207], v[76:79]
	v_mfma_f32_16x16x32_bf16 v[72:75], v[162:165], v[204:207], v[72:75]
	s_setprio 0
	s_barrier
	s_add_i32 s28, 0, 0x1c000
	s_add_i32 s29, s63, s70
	v_add_u32_e32 v132, s28, v170
	v_lshl_add_u64 v[224:225], v[224:225], 0, s[14:15]
	s_mov_b32 m0, s29
	ds_read_b128 v[208:211], v132
	ds_read_b128 v[212:215], v132 offset:1024
	ds_read_b128 v[216:219], v132 offset:2048
	ds_read_b128 v[220:223], v132 offset:3072
	global_load_lds_dwordx4 v[224:225], off
	v_lshl_add_u64 v[224:225], v[226:227], 0, s[14:15]
	s_add_i32 m0, s29, 0x2000
	s_nop 0
	global_load_lds_dwordx4 v[224:225], off
	s_barrier
	s_waitcnt lgkmcnt(0)
	s_setprio 1
	s_waitcnt lgkmcnt(0)
	v_mfma_f32_16x16x32_bf16 v[116:119], v[208:211], v[166:169], v[116:119]
	v_mfma_f32_16x16x32_bf16 v[112:115], v[216:219], v[166:169], v[112:115]
	v_mfma_f32_16x16x32_bf16 v[100:103], v[208:211], v[182:185], v[100:103]
	v_mfma_f32_16x16x32_bf16 v[96:99], v[216:219], v[182:185], v[96:99]
	v_mfma_f32_16x16x32_bf16 v[84:87], v[208:211], v[190:193], v[84:87]
	v_mfma_f32_16x16x32_bf16 v[80:83], v[216:219], v[190:193], v[80:83]
	v_mfma_f32_16x16x32_bf16 v[68:71], v[208:211], v[198:201], v[68:71]
	v_mfma_f32_16x16x32_bf16 v[64:67], v[216:219], v[198:201], v[64:67]
	v_mfma_f32_16x16x32_bf16 v[116:119], v[212:215], v[178:181], v[116:119]
	v_mfma_f32_16x16x32_bf16 v[112:115], v[220:223], v[178:181], v[112:115]
	v_mfma_f32_16x16x32_bf16 v[100:103], v[212:215], v[186:189], v[100:103]
	v_mfma_f32_16x16x32_bf16 v[96:99], v[220:223], v[186:189], v[96:99]
	v_mfma_f32_16x16x32_bf16 v[84:87], v[212:215], v[194:197], v[84:87]
	v_mfma_f32_16x16x32_bf16 v[80:83], v[220:223], v[194:197], v[80:83]
	v_mfma_f32_16x16x32_bf16 v[68:71], v[212:215], v[204:207], v[68:71]
	v_mfma_f32_16x16x32_bf16 v[64:67], v[220:223], v[204:207], v[64:67]
	s_setprio 0
	s_mov_b32 m0, s76
	v_lshl_add_u64 v[224:225], v[228:229], 0, s[14:15]
	s_barrier
	ds_read_b128 v[166:169], v175 offset:49152
	ds_read_b128 v[178:181], v175 offset:50176
	ds_read_b128 v[182:185], v175 offset:51200
	ds_read_b128 v[186:189], v175 offset:52224
	ds_read_b128 v[190:193], v175 offset:53248
	ds_read_b128 v[194:197], v175 offset:54272
	ds_read_b128 v[198:201], v175 offset:55296
	ds_read_b128 v[204:207], v175 offset:56320
	global_load_lds_dwordx4 v[224:225], off
	v_lshl_add_u64 v[224:225], v[230:231], 0, s[14:15]
	s_mov_b32 m0, s77
	s_nop 0
	global_load_lds_dwordx4 v[224:225], off
	s_barrier
; #define G_STAGE(bufoff, gbase, voff) do { _Pragma("unroll") for (int _i = 0; _i < 2; ++_i) \
;         __builtin_amdgcn_global_load_lds((const unsigned*)((const char*)(gbase) + (voff)[_i]), (LAS unsigned*)(lds + (bufoff) + ldsw + _i * 8192), 16, 0, 0); } while (0)
; #define G_MMA(ai, bj, At, Bt_) do { __builtin_amdgcn_s_setprio(1); _Pragma("unroll") for (int m = 0; m < 4; ++m) _Pragma("unroll") for (int n = 0; n < 2; ++n) _Pragma("unroll") for (int k = 0; k < 2; ++k) \
;         acc[ai][bj][m][n] = __builtin_amdgcn_mfma_f32_16x16x32_bf16(Bt_[n][k], At[m][k], acc[ai][bj][m][n], 0, 0, 0); __builtin_amdgcn_s_setprio(0); } while (0)
; #define G_WAIT_V(n) asm volatile("s_waitcnt vmcnt(" #n ")" ::: "memory")
; #define G_WAIT_L(n) asm volatile("s_waitcnt lgkmcnt(" #n ")" ::: "memory")
; #define G_BAR __builtin_amdgcn_s_barrier()
; #define G_SCHED __builtin_amdgcn_sched_barrier(0)
; template <class Epi, bool PERMROWS = false>
; DI void gemm_phase(LAS unsigned char* lds, const bf16_t* A, int lda, const bf16_t* Bt, int K, const Sched& S, const Epi& E) {
;     ...
;             G_BAR; G_WAIT_L(0); G_MMA(1, 0, At, B0); G_BAR; G_SCHED;
;             G_STAGE(G_SB(1, 1), b3 + hstepB, voffB);
;             G_WAIT_V(6); G_BAR; G_MMA(1, 1, At, B1); G_BAR;
;         }
;         E(acc, cur, wr, wc, fr, fq);
;     DI void operator()(const f32x4 (&acc)[2][2][4][2], const Unit& u, int wr, int wc, int fr, int fq) const {
;     ...
;                     const int colg = u.pn * BM + bj * HALF + wc * 32;
;                     f32x4 v0 = acc[ai][bj][m][0], v1 = acc[ai][bj][m][1];
;                     const int c0 = colg + 4 * fq;
;                     if (colg >= INW) continue;
;                     if (colg >= C_NAV && colg < C_CQ) {
	s_waitcnt lgkmcnt(0)
	s_setprio 1
	s_waitcnt lgkmcnt(0)
	v_mfma_f32_16x16x32_bf16 v[60:63], v[150:153], v[166:169], v[60:63]
	v_mfma_f32_16x16x32_bf16 v[56:59], v[158:161], v[166:169], v[56:59]
	v_mfma_f32_16x16x32_bf16 v[44:47], v[150:153], v[182:185], v[44:47]
	v_mfma_f32_16x16x32_bf16 v[40:43], v[158:161], v[182:185], v[40:43]
	v_mfma_f32_16x16x32_bf16 v[28:31], v[150:153], v[190:193], v[28:31]
	v_mfma_f32_16x16x32_bf16 v[24:27], v[158:161], v[190:193], v[24:27]
	v_mfma_f32_16x16x32_bf16 v[12:15], v[150:153], v[198:201], v[12:15]
	v_mfma_f32_16x16x32_bf16 v[8:11], v[158:161], v[198:201], v[8:11]
	v_mfma_f32_16x16x32_bf16 v[60:63], v[154:157], v[178:181], v[60:63]
	v_mfma_f32_16x16x32_bf16 v[56:59], v[162:165], v[178:181], v[56:59]
	v_mfma_f32_16x16x32_bf16 v[44:47], v[154:157], v[186:189], v[44:47]
	v_mfma_f32_16x16x32_bf16 v[40:43], v[162:165], v[186:189], v[40:43]
	v_mfma_f32_16x16x32_bf16 v[28:31], v[154:157], v[194:197], v[28:31]
	v_mfma_f32_16x16x32_bf16 v[24:27], v[162:165], v[194:197], v[24:27]
	v_mfma_f32_16x16x32_bf16 v[12:15], v[154:157], v[204:207], v[12:15]
	v_mfma_f32_16x16x32_bf16 v[8:11], v[162:165], v[204:207], v[8:11]
	s_setprio 0
	s_barrier
	s_add_u32 s12, s12, 0x80080
	s_addc_u32 s13, s13, 0
	s_add_i32 s28, s28, s70
	v_lshl_add_u64 v[150:151], s[12:13], 0, v[128:129]
	s_mov_b32 m0, s28
	s_nop 0
	global_load_lds_dwordx4 v[150:151], off
	v_lshl_add_u64 v[150:151], s[12:13], 0, v[130:131]
	s_add_i32 m0, s28, 0x2000
	s_nop 0
	global_load_lds_dwordx4 v[150:151], off
	s_waitcnt vmcnt(6)
	s_barrier
	s_setprio 1
	v_mfma_f32_16x16x32_bf16 v[52:55], v[208:211], v[166:169], v[52:55]
	v_mfma_f32_16x16x32_bf16 v[48:51], v[216:219], v[166:169], v[48:51]
	v_mfma_f32_16x16x32_bf16 v[36:39], v[208:211], v[182:185], v[36:39]
	v_mfma_f32_16x16x32_bf16 v[32:35], v[216:219], v[182:185], v[32:35]
	v_mfma_f32_16x16x32_bf16 v[20:23], v[208:211], v[190:193], v[20:23]
	v_mfma_f32_16x16x32_bf16 v[16:19], v[216:219], v[190:193], v[16:19]
	v_mfma_f32_16x16x32_bf16 v[4:7], v[208:211], v[198:201], v[4:7]
	v_mfma_f32_16x16x32_bf16 v[0:3], v[216:219], v[198:201], v[0:3]
	v_mfma_f32_16x16x32_bf16 v[52:55], v[212:215], v[178:181], v[52:55]
	v_mfma_f32_16x16x32_bf16 v[48:51], v[220:223], v[178:181], v[48:51]
	v_mfma_f32_16x16x32_bf16 v[36:39], v[212:215], v[186:189], v[36:39]
	v_mfma_f32_16x16x32_bf16 v[32:35], v[220:223], v[186:189], v[32:35]
	v_mfma_f32_16x16x32_bf16 v[20:23], v[212:215], v[194:197], v[20:23]
	v_mfma_f32_16x16x32_bf16 v[16:19], v[220:223], v[194:197], v[16:19]
	v_mfma_f32_16x16x32_bf16 v[4:7], v[212:215], v[204:207], v[4:7]
	v_mfma_f32_16x16x32_bf16 v[0:3], v[220:223], v[204:207], v[0:3]
	s_setprio 0
	s_add_i32 s62, s62, 2
	s_add_u32 s35, s35, 0x100
	s_addc_u32 s37, s37, 0
	s_add_u32 s10, s10, 0x100
	s_addc_u32 s11, s11, 0
	s_cmp_gt_u32 s62, 29
	s_barrier
	s_cbranch_scc0 .LBB0_534
	v_bfe_u32 v194, v202, 6, 2
	v_and_b32_e32 v169, 15, v202
	v_readfirstlane_b32 s9, v194
	s_lshl_b32 s35, s0, 8
	s_lshl_b32 s93, s9, 5
	s_add_u32 s35, s35, s93
	s_mov_b32 s37, 1
	s_cmpk_lt_u32 s35, 0x600
	s_cbranch_scc1 .Lip0_c0_d
	s_mov_b32 s37, 4
	s_cmpk_lt_u32 s35, 0x900
	s_cbranch_scc1 .Lip0_c0_d
	s_mov_b32 s37, 6
	s_cmpk_lt_u32 s35, 0xd00
	s_cbranch_scc1 .Lip0_c0_d
	s_mov_b32 s37, 7
	s_cmpk_lt_u32 s35, 0xd40
	s_cbranch_scc1 .Lip0_c0_d
	s_mov_b32 s37, 2
	s_cmpk_lt_u32 s35, 0xfc0
	s_cbranch_scc1 .Lip0_c0_d
	s_mov_b32 s37, 3
	s_cmpk_lt_u32 s35, 0x1240
	s_cbranch_scc1 .Lip0_c0_d
	s_mov_b32 s37, 5
	s_cmpk_lt_u32 s35, 0x14c0
	s_cbranch_scc1 .Lip0_c0_d
	s_mov_b32 s37, 1
	s_cmpk_lt_u32 s35, 0x1740
	s_cbranch_scc1 .Lip0_c0_d
	s_mov_b32 s37, 0
.Lip0_c0_d:
	s_add_u32 s35, s35, 0x80
	s_mov_b32 s92, 1
	s_cmpk_lt_u32 s35, 0x600
	s_cbranch_scc1 .Lip0_c1_d
	s_mov_b32 s92, 4
	s_cmpk_lt_u32 s35, 0x900
	s_cbranch_scc1 .Lip0_c1_d
	s_mov_b32 s92, 6
	s_cmpk_lt_u32 s35, 0xd00
	s_cbranch_scc1 .Lip0_c1_d
	s_mov_b32 s92, 7
	s_cmpk_lt_u32 s35, 0xd40
	s_cbranch_scc1 .Lip0_c1_d
	s_mov_b32 s92, 2
	s_cmpk_lt_u32 s35, 0xfc0
	s_cbranch_scc1 .Lip0_c1_d
	s_mov_b32 s92, 3
	s_cmpk_lt_u32 s35, 0x1240
	s_cbranch_scc1 .Lip0_c1_d
	s_mov_b32 s92, 5
	s_cmpk_lt_u32 s35, 0x14c0
	s_cbranch_scc1 .Lip0_c1_d
	s_mov_b32 s92, 1
	s_cmpk_lt_u32 s35, 0x1740
	s_cbranch_scc1 .Lip0_c1_d
	s_mov_b32 s92, 0
; DI void st_bf16x4(bf16_t* p, f32x4 v) { u32x2 w; w.x = cvt_pk_bf16(v[0], v[1]); w.y = cvt_pk_bf16(v[2], v[3]); *(u32x2*)p = w; }
;     DI void operator()(const f32x4 (&acc)[2][2][4][2], const Unit& u, int wr, int wc, int fr, int fq) const {
;         bf16_t* P = (bf16_t*)(ws + WS_P);
;         const int b = u.pm / 9;
; #pragma unroll
;         for (int ai = 0; ai < 2; ++ai)
; #pragma unroll
;             for (int m = 0; m < 4; ++m) {
;                 const int row = u.pm * BM + ai * HALF + wr * 64 + m * 16 + fr;
;                 const int r = row - b * RB; const bool lat = r >= CL; const int t = r - CL;
; #pragma unroll
;                 for (int bj = 0; bj < 2; ++bj) {
;                     const int colg = u.pn * BM + bj * HALF + wc * 32;
;                     f32x4 v0 = acc[ai][bj][m][0], v1 = acc[ai][bj][m][1];
;                     const int c0 = colg + 4 * fq;
;                     if (colg >= INW) continue;
;                     if (colg >= C_NAV && colg < C_CQ) {
;                         st_tr16x32(spare + (wr * 4 + wc) * 1024, (bf16_t*)(ws + WS_VTNA) + ((size_t)b * 768 + (colg - C_NAV)) * RB + (r - fr), v0, v1, fr, fq, fq * 16 + fr);
;                     } else if (colg >= C_RV && colg < C_RG) {
;                         st_tr16x32(spare + (wr * 4 + wc) * 1024, (bf16_t*)(ws + WS_VTR) + ((size_t)b * 640 + (colg - C_RV)) * RB + (r - fr), v0, v1, fr, fq, fq * 16 + fr);
;                     } else if (colg >= C_KPE && colg < C_RQ) {
;                         if (lat) rope4(v0, v1, (const float*)(ws + WS_TABM) + ((size_t)t * 32 + ((colg - C_KPE) >> 5) * 16 + 4 * fq) * 2);
;                         bf16_t* kp = (bf16_t*)(ws + WS_KPE) + (size_t)row * 64 + (c0 - C_KPE);
;                         st_bf16x4(kp, v0); st_bf16x4(kp + 16, v1);
;                     } else if (colg >= C_RQ && colg < C_RV) {
;                         if (lat) rope4(v0, v1, (const float*)(ws + WS_TABR) + ((size_t)t * 64 + (((colg - C_RQ) & 127) >> 5) * 16 + 4 * fq) * 2);
.Lip0_c1_d:
	s_sub_u32 s35, s35, 0x80
	v_bfe_u32 v194, v202, 8, 1
	v_lshl_add_u32 v195, v194, 6, v169
	v_bfe_u32 v196, v202, 4, 2
	v_and_b32_e32 v197, 63, v202
	s_mul_i32 s32, s8, 57
	s_lshr_b32 s32, s32, 9
	s_mul_i32 s93, s32, 9
	s_sub_u32 s27, s8, s93
	v_mul_u32_u24_e32 v169, 0x3000, v195
	v_lshl_add_u32 v150, v196, 3, v169
	v_add_u32_e32 v151, 0x30000, v150
	v_add_u32_e32 v152, 0x60000, v150
	v_add_u32_e32 v153, 0x90000, v150
	v_add_u32_e32 v154, 0x180000, v150
	v_add_u32_e32 v155, 0x1b0000, v150
	v_add_u32_e32 v156, 0x1e0000, v150
	v_add_u32_e32 v157, 0x210000, v150
	v_lshrrev_b32_e32 v169, 6, v202
	v_lshlrev_b32_e32 v169, 10, v169
	v_add_u32_e32 v169, 0x20000, v169
	v_and_b32_e32 v194, 15, v202
	v_lshl_add_u32 v167, v196, 7, v169
	v_lshl_add_u32 v167, v194, 1, v167
	v_lshrrev_b32_e32 v194, 1, v197
	v_lshl_add_u32 v168, v194, 5, v169
	v_and_b32_e32 v169, 1, v197
	v_lshl_add_u32 v168, v169, 4, v168
	v_mul_u32_u24_e32 v166, 0x1200, v194
	v_lshl_add_u32 v166, v169, 4, v166
	v_bfe_u32 v169, v202, 8, 1
	v_lshl_add_u32 v166, v169, 7, v166
	s_cmp_eq_u32 s37, 0
	s_cbranch_scc1 .Lip0_k0_end
	s_cmp_eq_u32 s37, 1
	s_cbranch_scc1 .Lip0_k0_plain
	s_cmp_eq_u32 s37, 4
	s_cbranch_scc1 .Lip0_k0_nav
	s_cmp_eq_u32 s37, 5
	s_cbranch_scc1 .Lip0_k0_rv
	s_cmp_eq_u32 s37, 6
	s_cbranch_scc1 .Lip0_k0_ssq
	s_cmp_eq_u32 s37, 7
	s_cbranch_scc1 .Lip0_k0_kpe
	s_cmp_eq_u32 s27, 0
	s_cbranch_scc1 .Lip0_nr0
	s_sub_u32 s97, s35, 0xd40
	s_and_b32 s97, s97, 0x7f
	s_lshr_b32 s97, s97, 5
	s_lshl_b32 s97, s97, 7
	s_sub_u32 s93, s27, 1
	s_lshl_b32 s93, s93, 17
	s_add_u32 s93, s93, s97
	v_lshlrev_b32_e32 v169, 5, v196
	v_lshl_add_u32 v158, v195, 9, v169
	v_add_u32_e32 v158, s93, v158
	v_add_u32_e32 v159, 0x2000, v158
	v_add_u32_e32 v160, 0x4000, v158
	v_add_u32_e32 v161, 0x6000, v158
	v_add_u32_e32 v162, 0x10000, v158
	v_add_u32_e32 v163, 0x12000, v158
	v_add_u32_e32 v164, 0x14000, v158
	v_add_u32_e32 v165, 0x16000, v158
	s_add_u32 s10, s50, 0x100000
	s_addc_u32 s11, s51, 0
	global_load_dwordx4 v[204:207], v158, s[10:11]
	global_load_dwordx4 v[208:211], v158, s[10:11] offset:16
	global_load_dwordx4 v[212:215], v159, s[10:11]
	global_load_dwordx4 v[216:219], v159, s[10:11] offset:16
	global_load_dwordx4 v[220:223], v160, s[10:11]
	global_load_dwordx4 v[224:227], v160, s[10:11] offset:16
	global_load_dwordx4 v[228:231], v161, s[10:11]
	global_load_dwordx4 v[232:235], v161, s[10:11] offset:16
	global_load_dwordx4 v[236:239], v162, s[10:11]
	global_load_dwordx4 v[240:243], v162, s[10:11] offset:16
	global_load_dwordx4 v[244:247], v163, s[10:11]
	global_load_dwordx4 v[248:251], v163, s[10:11] offset:16
	global_load_dwordx4 v[178:181], v164, s[10:11]
	global_load_dwordx4 v[182:185], v164, s[10:11] offset:16
	global_load_dwordx4 v[186:189], v165, s[10:11]
	global_load_dwordx4 v[190:193], v165, s[10:11] offset:16
	s_waitcnt vmcnt(0)
	v_mul_f32_e32 v169, v124, v205
	v_mul_f32_e32 v124, v124, v204
	v_fma_f32 v124, -v120, v205, v124
	v_fma_f32 v120, v120, v204, v169
	v_mul_f32_e32 v169, v125, v207
	v_mul_f32_e32 v125, v125, v206
	v_fma_f32 v125, -v121, v207, v125
	v_fma_f32 v121, v121, v206, v169
	v_mul_f32_e32 v169, v126, v209
	v_mul_f32_e32 v126, v126, v208
	v_fma_f32 v126, -v122, v209, v126
	v_fma_f32 v122, v122, v208, v169
	v_mul_f32_e32 v169, v127, v211
	v_mul_f32_e32 v127, v127, v210
	v_fma_f32 v127, -v123, v211, v127
	v_fma_f32 v123, v123, v210, v169
	v_mul_f32_e32 v169, v108, v213
	v_mul_f32_e32 v108, v108, v212
	v_fma_f32 v108, -v104, v213, v108
	v_fma_f32 v104, v104, v212, v169
	v_mul_f32_e32 v169, v109, v215
	v_mul_f32_e32 v109, v109, v214
	v_fma_f32 v109, -v105, v215, v109
	v_fma_f32 v105, v105, v214, v169
	v_mul_f32_e32 v169, v110, v217
	v_mul_f32_e32 v110, v110, v216
	v_fma_f32 v110, -v106, v217, v110
	v_fma_f32 v106, v106, v216, v169
	v_mul_f32_e32 v169, v111, v219
	v_mul_f32_e32 v111, v111, v218
	v_fma_f32 v111, -v107, v219, v111
	v_fma_f32 v107, v107, v218, v169
	v_mul_f32_e32 v169, v92, v221
	v_mul_f32_e32 v92, v92, v220
	v_fma_f32 v92, -v88, v221, v92
	v_fma_f32 v88, v88, v220, v169
	v_mul_f32_e32 v169, v93, v223
	v_mul_f32_e32 v93, v93, v222
	v_fma_f32 v93, -v89, v223, v93
	v_fma_f32 v89, v89, v222, v169
	v_mul_f32_e32 v169, v94, v225
	v_mul_f32_e32 v94, v94, v224
	v_fma_f32 v94, -v90, v225, v94
	v_fma_f32 v90, v90, v224, v169
	v_mul_f32_e32 v169, v95, v227
	v_mul_f32_e32 v95, v95, v226
	v_fma_f32 v95, -v91, v227, v95
	v_fma_f32 v91, v91, v226, v169
	v_mul_f32_e32 v169, v76, v229
	v_mul_f32_e32 v76, v76, v228
	v_fma_f32 v76, -v72, v229, v76
	v_fma_f32 v72, v72, v228, v169
	v_mul_f32_e32 v169, v77, v231
	v_mul_f32_e32 v77, v77, v230
	v_fma_f32 v77, -v73, v231, v77
	v_fma_f32 v73, v73, v230, v169
	v_mul_f32_e32 v169, v78, v233
	v_mul_f32_e32 v78, v78, v232
	v_fma_f32 v78, -v74, v233, v78
	v_fma_f32 v74, v74, v232, v169
	v_mul_f32_e32 v169, v79, v235
	v_mul_f32_e32 v79, v79, v234
	v_fma_f32 v79, -v75, v235, v79
	v_fma_f32 v75, v75, v234, v169
	v_mul_f32_e32 v169, v60, v237
	v_mul_f32_e32 v60, v60, v236
	v_fma_f32 v60, -v56, v237, v60
	v_fma_f32 v56, v56, v236, v169
	v_mul_f32_e32 v169, v61, v239
	v_mul_f32_e32 v61, v61, v238
	v_fma_f32 v61, -v57, v239, v61
	v_fma_f32 v57, v57, v238, v169
	v_mul_f32_e32 v169, v62, v241
	v_mul_f32_e32 v62, v62, v240
	v_fma_f32 v62, -v58, v241, v62
	v_fma_f32 v58, v58, v240, v169
	v_mul_f32_e32 v169, v63, v243
	v_mul_f32_e32 v63, v63, v242
	v_fma_f32 v63, -v59, v243, v63
	v_fma_f32 v59, v59, v242, v169
	v_mul_f32_e32 v169, v44, v245
	v_mul_f32_e32 v44, v44, v244
	v_fma_f32 v44, -v40, v245, v44
	v_fma_f32 v40, v40, v244, v169
	v_mul_f32_e32 v169, v45, v247
	v_mul_f32_e32 v45, v45, v246
	v_fma_f32 v45, -v41, v247, v45
	v_fma_f32 v41, v41, v246, v169
	v_mul_f32_e32 v169, v46, v249
	v_mul_f32_e32 v46, v46, v248
	v_fma_f32 v46, -v42, v249, v46
	v_fma_f32 v42, v42, v248, v169
	v_mul_f32_e32 v169, v47, v251
	v_mul_f32_e32 v47, v47, v250
	v_fma_f32 v47, -v43, v251, v47
	v_fma_f32 v43, v43, v250, v169
	v_mul_f32_e32 v169, v28, v179
	v_mul_f32_e32 v28, v28, v178
	v_fma_f32 v28, -v24, v179, v28
	v_fma_f32 v24, v24, v178, v169
	v_mul_f32_e32 v169, v29, v181
	v_mul_f32_e32 v29, v29, v180
	v_fma_f32 v29, -v25, v181, v29
	v_fma_f32 v25, v25, v180, v169
	v_mul_f32_e32 v169, v30, v183
	v_mul_f32_e32 v30, v30, v182
	v_fma_f32 v30, -v26, v183, v30
	v_fma_f32 v26, v26, v182, v169
	v_mul_f32_e32 v169, v31, v185
	v_mul_f32_e32 v31, v31, v184
	v_fma_f32 v31, -v27, v185, v31
	v_fma_f32 v27, v27, v184, v169
	v_mul_f32_e32 v169, v12, v187
	v_mul_f32_e32 v12, v12, v186
	v_fma_f32 v12, -v8, v187, v12
	v_fma_f32 v8, v8, v186, v169
	v_mul_f32_e32 v169, v13, v189
	v_mul_f32_e32 v13, v13, v188
	v_fma_f32 v13, -v9, v189, v13
	v_fma_f32 v9, v9, v188, v169
	v_mul_f32_e32 v169, v14, v191
	v_mul_f32_e32 v14, v14, v190
	v_fma_f32 v14, -v10, v191, v14
	v_fma_f32 v10, v10, v190, v169
	v_mul_f32_e32 v169, v15, v193
	v_mul_f32_e32 v15, v15, v192
	v_fma_f32 v15, -v11, v193, v15
	v_fma_f32 v11, v11, v192, v169

; DI void rope4(f32x4& v0, f32x4& v1, const float* tab  ) {
;     const f32x4 t0 = *(const f32x4*)tab, t1 = *(const f32x4*)(tab + 4);
;     const float c[4] = {t0[0], t0[2], t1[0], t1[2]}, s[4] = {t0[1], t0[3], t1[1], t1[3]};
; #pragma unroll
;     for (int j = 0; j < 4; ++j) { const float a = v0[j], b = v1[j]; v0[j] = a * c[j] - b * s[j]; v1[j] = b * c[j] + a * s[j]; }
; }
;     DI void operator()(const f32x4 (&acc)[2][2][4][2], const Unit& u, int wr, int wc, int fr, int fq) const {
;     ...
;                     } else if (colg >= C_KPE && colg < C_RQ) {
;                         if (lat) rope4(v0, v1, (const float*)(ws + WS_TABM) + ((size_t)t * 32 + ((colg - C_KPE) >> 5) * 16 + 4 * fq) * 2);
.Lip0_k0_kpe:
	s_cmp_eq_u32 s27, 0
	s_cbranch_scc1 .Lip0_nr0k
	s_sub_u32 s97, s35, 0xd00
	s_and_b32 s97, s97, 0x7f
	s_lshr_b32 s97, s97, 5
	s_lshl_b32 s97, s97, 7
	s_sub_u32 s93, s27, 1
	s_lshl_b32 s93, s93, 16
	s_add_u32 s93, s93, s97
	v_lshlrev_b32_e32 v169, 5, v196
	v_lshl_add_u32 v158, v195, 8, v169
	v_add_u32_e32 v158, s93, v158
	v_add_u32_e32 v159, 0x1000, v158
	v_add_u32_e32 v160, 0x2000, v158
	v_add_u32_e32 v161, 0x3000, v158
	v_add_u32_e32 v162, 0x8000, v158
	v_add_u32_e32 v163, 0x9000, v158
	v_add_u32_e32 v164, 0xa000, v158
	v_add_u32_e32 v165, 0xb000, v158
	s_add_u32 s10, s50, 0x80000
	s_addc_u32 s11, s51, 0
	global_load_dwordx4 v[204:207], v158, s[10:11]
	global_load_dwordx4 v[208:211], v158, s[10:11] offset:16
	global_load_dwordx4 v[212:215], v159, s[10:11]
	global_load_dwordx4 v[216:219], v159, s[10:11] offset:16
	global_load_dwordx4 v[220:223], v160, s[10:11]
	global_load_dwordx4 v[224:227], v160, s[10:11] offset:16
	global_load_dwordx4 v[228:231], v161, s[10:11]
	global_load_dwordx4 v[232:235], v161, s[10:11] offset:16
	global_load_dwordx4 v[236:239], v162, s[10:11]
	global_load_dwordx4 v[240:243], v162, s[10:11] offset:16
	global_load_dwordx4 v[244:247], v163, s[10:11]
	global_load_dwordx4 v[248:251], v163, s[10:11] offset:16
	global_load_dwordx4 v[178:181], v164, s[10:11]
	global_load_dwordx4 v[182:185], v164, s[10:11] offset:16
	global_load_dwordx4 v[186:189], v165, s[10:11]
	global_load_dwordx4 v[190:193], v165, s[10:11] offset:16
	s_waitcnt vmcnt(0)
	v_mul_f32_e32 v169, v124, v205
	v_mul_f32_e32 v124, v124, v204
	v_fma_f32 v124, -v120, v205, v124
	v_fma_f32 v120, v120, v204, v169
	v_mul_f32_e32 v169, v125, v207
	v_mul_f32_e32 v125, v125, v206
	v_fma_f32 v125, -v121, v207, v125
	v_fma_f32 v121, v121, v206, v169
	v_mul_f32_e32 v169, v126, v209
	v_mul_f32_e32 v126, v126, v208
	v_fma_f32 v126, -v122, v209, v126
	v_fma_f32 v122, v122, v208, v169
	v_mul_f32_e32 v169, v127, v211
	v_mul_f32_e32 v127, v127, v210
	v_fma_f32 v127, -v123, v211, v127
	v_fma_f32 v123, v123, v210, v169
	v_mul_f32_e32 v169, v108, v213
	v_mul_f32_e32 v108, v108, v212
	v_fma_f32 v108, -v104, v213, v108
	v_fma_f32 v104, v104, v212, v169
	v_mul_f32_e32 v169, v109, v215
	v_mul_f32_e32 v109, v109, v214
	v_fma_f32 v109, -v105, v215, v109
	v_fma_f32 v105, v105, v214, v169
	v_mul_f32_e32 v169, v110, v217
	v_mul_f32_e32 v110, v110, v216
	v_fma_f32 v110, -v106, v217, v110
	v_fma_f32 v106, v106, v216, v169
	v_mul_f32_e32 v169, v111, v219
	v_mul_f32_e32 v111, v111, v218
	v_fma_f32 v111, -v107, v219, v111
	v_fma_f32 v107, v107, v218, v169
	v_mul_f32_e32 v169, v92, v221
	v_mul_f32_e32 v92, v92, v220
	v_fma_f32 v92, -v88, v221, v92
	v_fma_f32 v88, v88, v220, v169
	v_mul_f32_e32 v169, v93, v223
	v_mul_f32_e32 v93, v93, v222
	v_fma_f32 v93, -v89, v223, v93
	v_fma_f32 v89, v89, v222, v169
	v_mul_f32_e32 v169, v94, v225
	v_mul_f32_e32 v94, v94, v224
	v_fma_f32 v94, -v90, v225, v94
	v_fma_f32 v90, v90, v224, v169
	v_mul_f32_e32 v169, v95, v227
	v_mul_f32_e32 v95, v95, v226
	v_fma_f32 v95, -v91, v227, v95
	v_fma_f32 v91, v91, v226, v169
	v_mul_f32_e32 v169, v76, v229
	v_mul_f32_e32 v76, v76, v228
	v_fma_f32 v76, -v72, v229, v76
	v_fma_f32 v72, v72, v228, v169
	v_mul_f32_e32 v169, v77, v231
	v_mul_f32_e32 v77, v77, v230
	v_fma_f32 v77, -v73, v231, v77
	v_fma_f32 v73, v73, v230, v169
	v_mul_f32_e32 v169, v78, v233
	v_mul_f32_e32 v78, v78, v232
	v_fma_f32 v78, -v74, v233, v78
	v_fma_f32 v74, v74, v232, v169
	v_mul_f32_e32 v169, v79, v235
	v_mul_f32_e32 v79, v79, v234
	v_fma_f32 v79, -v75, v235, v79
	v_fma_f32 v75, v75, v234, v169
	v_mul_f32_e32 v169, v60, v237
	v_mul_f32_e32 v60, v60, v236
	v_fma_f32 v60, -v56, v237, v60
	v_fma_f32 v56, v56, v236, v169
	v_mul_f32_e32 v169, v61, v239
	v_mul_f32_e32 v61, v61, v238
	v_fma_f32 v61, -v57, v239, v61
	v_fma_f32 v57, v57, v238, v169
	v_mul_f32_e32 v169, v62, v241
	v_mul_f32_e32 v62, v62, v240
	v_fma_f32 v62, -v58, v241, v62
	v_fma_f32 v58, v58, v240, v169
	v_mul_f32_e32 v169, v63, v243
	v_mul_f32_e32 v63, v63, v242
	v_fma_f32 v63, -v59, v243, v63
	v_fma_f32 v59, v59, v242, v169
	v_mul_f32_e32 v169, v44, v245
	v_mul_f32_e32 v44, v44, v244
	v_fma_f32 v44, -v40, v245, v44
	v_fma_f32 v40, v40, v244, v169
	v_mul_f32_e32 v169, v45, v247
	v_mul_f32_e32 v45, v45, v246
	v_fma_f32 v45, -v41, v247, v45
	v_fma_f32 v41, v41, v246, v169
	v_mul_f32_e32 v169, v46, v249
	v_mul_f32_e32 v46, v46, v248
	v_fma_f32 v46, -v42, v249, v46
	v_fma_f32 v42, v42, v248, v169
	v_mul_f32_e32 v169, v47, v251
	v_mul_f32_e32 v47, v47, v250
	v_fma_f32 v47, -v43, v251, v47
	v_fma_f32 v43, v43, v250, v169
	v_mul_f32_e32 v169, v28, v179
	v_mul_f32_e32 v28, v28, v178
	v_fma_f32 v28, -v24, v179, v28
	v_fma_f32 v24, v24, v178, v169
	v_mul_f32_e32 v169, v29, v181
	v_mul_f32_e32 v29, v29, v180
	v_fma_f32 v29, -v25, v181, v29
	v_fma_f32 v25, v25, v180, v169
	v_mul_f32_e32 v169, v30, v183
	v_mul_f32_e32 v30, v30, v182
	v_fma_f32 v30, -v26, v183, v30
	v_fma_f32 v26, v26, v182, v169
	v_mul_f32_e32 v169, v31, v185
	v_mul_f32_e32 v31, v31, v184
	v_fma_f32 v31, -v27, v185, v31
	v_fma_f32 v27, v27, v184, v169
	v_mul_f32_e32 v169, v12, v187
	v_mul_f32_e32 v12, v12, v186
	v_fma_f32 v12, -v8, v187, v12
	v_fma_f32 v8, v8, v186, v169
	v_mul_f32_e32 v169, v13, v189
	v_mul_f32_e32 v13, v13, v188
	v_fma_f32 v13, -v9, v189, v13
	v_fma_f32 v9, v9, v188, v169
	v_mul_f32_e32 v169, v14, v191
	v_mul_f32_e32 v14, v14, v190
	v_fma_f32 v14, -v10, v191, v14
	v_fma_f32 v10, v10, v190, v169
	v_mul_f32_e32 v169, v15, v193
	v_mul_f32_e32 v15, v15, v192
	v_fma_f32 v15, -v11, v193, v15
	v_fma_f32 v11, v11, v192, v169
; DI void st_bf16x4(bf16_t* p, f32x4 v) { u32x2 w; w.x = cvt_pk_bf16(v[0], v[1]); w.y = cvt_pk_bf16(v[2], v[3]); *(u32x2*)p = w; }
;     DI void operator()(const f32x4 (&acc)[2][2][4][2], const Unit& u, int wr, int wc, int fr, int fq) const {
;     ...
;                     } else if (colg >= C_KPE && colg < C_RQ) {
;                         if (lat) rope4(v0, v1, (const float*)(ws + WS_TABM) + ((size_t)t * 32 + ((colg - C_KPE) >> 5) * 16 + 4 * fq) * 2);
;                         bf16_t* kp = (bf16_t*)(ws + WS_KPE) + (size_t)row * 64 + (c0 - C_KPE);
;                         st_bf16x4(kp, v0); st_bf16x4(kp + 16, v1);
.Lip0_nr0k:
	s_lshl_b32 s93, s8, 15
	s_add_u32 s10, s50, 0x1cb00000
	s_addc_u32 s11, s51, 0
	s_add_u32 s10, s10, s93
	s_addc_u32 s11, s11, 0
	s_sub_u32 s93, s35, 0xd00
	s_lshl_b32 s93, s93, 1
	s_add_u32 s10, s10, s93
	s_addc_u32 s11, s11, 0
	v_lshlrev_b32_e32 v158, 7, v195
	v_lshl_add_u32 v158, v196, 3, v158
	v_add_u32_e32 v159, 0x800, v158
	v_add_u32_e32 v160, 0x1000, v158
	v_add_u32_e32 v161, 0x1800, v158
	v_add_u32_e32 v162, 0x4000, v158
	v_add_u32_e32 v163, 0x4800, v158
	v_add_u32_e32 v164, 0x5000, v158
	v_add_u32_e32 v165, 0x5800, v158
	v_cvt_pk_bf16_f32 v124, v124, v125
	v_cvt_pk_bf16_f32 v125, v126, v127
	global_store_dwordx2 v158, v[124:125], s[10:11] offset:0
	v_cvt_pk_bf16_f32 v120, v120, v121
	v_cvt_pk_bf16_f32 v121, v122, v123
	global_store_dwordx2 v158, v[120:121], s[10:11] offset:32
	v_cvt_pk_bf16_f32 v108, v108, v109
	v_cvt_pk_bf16_f32 v109, v110, v111
	global_store_dwordx2 v159, v[108:109], s[10:11] offset:0
	v_cvt_pk_bf16_f32 v104, v104, v105
	v_cvt_pk_bf16_f32 v105, v106, v107
	global_store_dwordx2 v159, v[104:105], s[10:11] offset:32
	v_cvt_pk_bf16_f32 v92, v92, v93
	v_cvt_pk_bf16_f32 v93, v94, v95
	global_store_dwordx2 v160, v[92:93], s[10:11] offset:0
	v_cvt_pk_bf16_f32 v88, v88, v89
	v_cvt_pk_bf16_f32 v89, v90, v91
	global_store_dwordx2 v160, v[88:89], s[10:11] offset:32
	v_cvt_pk_bf16_f32 v76, v76, v77
	v_cvt_pk_bf16_f32 v77, v78, v79
	global_store_dwordx2 v161, v[76:77], s[10:11] offset:0
	v_cvt_pk_bf16_f32 v72, v72, v73
	v_cvt_pk_bf16_f32 v73, v74, v75
	global_store_dwordx2 v161, v[72:73], s[10:11] offset:32
	v_cvt_pk_bf16_f32 v60, v60, v61
	v_cvt_pk_bf16_f32 v61, v62, v63
	global_store_dwordx2 v162, v[60:61], s[10:11] offset:0
	v_cvt_pk_bf16_f32 v56, v56, v57
	v_cvt_pk_bf16_f32 v57, v58, v59
	global_store_dwordx2 v162, v[56:57], s[10:11] offset:32
	v_cvt_pk_bf16_f32 v44, v44, v45
	v_cvt_pk_bf16_f32 v45, v46, v47
	global_store_dwordx2 v163, v[44:45], s[10:11] offset:0
	v_cvt_pk_bf16_f32 v40, v40, v41
	v_cvt_pk_bf16_f32 v41, v42, v43
	global_store_dwordx2 v163, v[40:41], s[10:11] offset:32
	v_cvt_pk_bf16_f32 v28, v28, v29
	v_cvt_pk_bf16_f32 v29, v30, v31
	global_store_dwordx2 v164, v[28:29], s[10:11] offset:0
	v_cvt_pk_bf16_f32 v24, v24, v25
	v_cvt_pk_bf16_f32 v25, v26, v27
	global_store_dwordx2 v164, v[24:25], s[10:11] offset:32
	v_cvt_pk_bf16_f32 v12, v12, v13
	v_cvt_pk_bf16_f32 v13, v14, v15
	global_store_dwordx2 v165, v[12:13], s[10:11] offset:0
	v_cvt_pk_bf16_f32 v8, v8, v9
	v_cvt_pk_bf16_f32 v9, v10, v11
	global_store_dwordx2 v165, v[8:9], s[10:11] offset:32
	s_branch .Lip0_k0_end
; DI void st_bf16x4(bf16_t* p, f32x4 v) { u32x2 w; w.x = cvt_pk_bf16(v[0], v[1]); w.y = cvt_pk_bf16(v[2], v[3]); *(u32x2*)p = w; }
;     DI void operator()(const f32x4 (&acc)[2][2][4][2], const Unit& u, int wr, int wc, int fr, int fq) const {
;     ...
;                 for (int bj = 0; bj < 2; ++bj) {
;                     const int colg = u.pn * BM + bj * HALF + wc * 32;
;                     f32x4 v0 = acc[ai][bj][m][0], v1 = acc[ai][bj][m][1];
;                     const int c0 = colg + 4 * fq;
;                     if (colg >= INW) continue;
;                     if (colg >= C_NAV && colg < C_CQ) {
;                         st_tr16x32(spare + (wr * 4 + wc) * 1024, (bf16_t*)(ws + WS_VTNA) + ((size_t)b * 768 + (colg - C_NAV)) * RB + (r - fr), v0, v1, fr, fq, fq * 16 + fr);
;                     } else if (colg >= C_RV && colg < C_RG) {
;                         st_tr16x32(spare + (wr * 4 + wc) * 1024, (bf16_t*)(ws + WS_VTR) + ((size_t)b * 640 + (colg - C_RV)) * RB + (r - fr), v0, v1, fr, fq, fq * 16 + fr);
;                     } else if (colg >= C_KPE && colg < C_RQ) {
;                         if (lat) rope4(v0, v1, (const float*)(ws + WS_TABM) + ((size_t)t * 32 + ((colg - C_KPE) >> 5) * 16 + 4 * fq) * 2);
;                         bf16_t* kp = (bf16_t*)(ws + WS_KPE) + (size_t)row * 64 + (c0 - C_KPE);
;                         st_bf16x4(kp, v0); st_bf16x4(kp + 16, v1);
;                     } else if (colg >= C_RQ && colg < C_RV) {
;                         if (lat) rope4(v0, v1, (const float*)(ws + WS_TABR) + ((size_t)t * 64 + (((colg - C_RQ) & 127) >> 5) * 16 + 4 * fq) * 2);
.Lip0_k0_end:
	s_add_u32 s35, s35, 0x80
	s_cmp_eq_u32 s92, 0
	s_cbranch_scc1 .Lip0_k1_end
	s_cmp_eq_u32 s92, 1
	s_cbranch_scc1 .Lip0_k1_plain
	s_cmp_eq_u32 s92, 4
	s_cbranch_scc1 .Lip0_k1_nav
	s_cmp_eq_u32 s92, 5
	s_cbranch_scc1 .Lip0_k1_rv
	s_cmp_eq_u32 s92, 6
	s_cbranch_scc1 .Lip0_k1_ssq
	s_cmp_eq_u32 s92, 7
	s_cbranch_scc1 .Lip0_k1_kpe
	s_cmp_eq_u32 s27, 0
	s_cbranch_scc1 .Lip0_nr1
	s_sub_u32 s97, s35, 0xd40
	s_and_b32 s97, s97, 0x7f
	s_lshr_b32 s97, s97, 5
	s_lshl_b32 s97, s97, 7
	s_sub_u32 s93, s27, 1
	s_lshl_b32 s93, s93, 17
	s_add_u32 s93, s93, s97
	v_lshlrev_b32_e32 v169, 5, v196
	v_lshl_add_u32 v158, v195, 9, v169
	v_add_u32_e32 v158, s93, v158
	v_add_u32_e32 v159, 0x2000, v158
	v_add_u32_e32 v160, 0x4000, v158
	v_add_u32_e32 v161, 0x6000, v158
	v_add_u32_e32 v162, 0x10000, v158
	v_add_u32_e32 v163, 0x12000, v158
	v_add_u32_e32 v164, 0x14000, v158
	v_add_u32_e32 v165, 0x16000, v158
	s_add_u32 s10, s50, 0x100000
	s_addc_u32 s11, s51, 0
	global_load_dwordx4 v[204:207], v158, s[10:11]
	global_load_dwordx4 v[208:211], v158, s[10:11] offset:16
	global_load_dwordx4 v[212:215], v159, s[10:11]
	global_load_dwordx4 v[216:219], v159, s[10:11] offset:16
	global_load_dwordx4 v[220:223], v160, s[10:11]
	global_load_dwordx4 v[224:227], v160, s[10:11] offset:16
	global_load_dwordx4 v[228:231], v161, s[10:11]
	global_load_dwordx4 v[232:235], v161, s[10:11] offset:16
	global_load_dwordx4 v[236:239], v162, s[10:11]
	global_load_dwordx4 v[240:243], v162, s[10:11] offset:16
	global_load_dwordx4 v[244:247], v163, s[10:11]
	global_load_dwordx4 v[248:251], v163, s[10:11] offset:16
	global_load_dwordx4 v[178:181], v164, s[10:11]
	global_load_dwordx4 v[182:185], v164, s[10:11] offset:16
	global_load_dwordx4 v[186:189], v165, s[10:11]
	global_load_dwordx4 v[190:193], v165, s[10:11] offset:16
	s_waitcnt vmcnt(0)
	v_mul_f32_e32 v169, v116, v205
	v_mul_f32_e32 v116, v116, v204
	v_fma_f32 v116, -v112, v205, v116
	v_fma_f32 v112, v112, v204, v169
	v_mul_f32_e32 v169, v117, v207
	v_mul_f32_e32 v117, v117, v206
	v_fma_f32 v117, -v113, v207, v117
	v_fma_f32 v113, v113, v206, v169
	v_mul_f32_e32 v169, v118, v209
	v_mul_f32_e32 v118, v118, v208
	v_fma_f32 v118, -v114, v209, v118
	v_fma_f32 v114, v114, v208, v169
	v_mul_f32_e32 v169, v119, v211
	v_mul_f32_e32 v119, v119, v210
	v_fma_f32 v119, -v115, v211, v119
	v_fma_f32 v115, v115, v210, v169
	v_mul_f32_e32 v169, v100, v213
	v_mul_f32_e32 v100, v100, v212
	v_fma_f32 v100, -v96, v213, v100
	v_fma_f32 v96, v96, v212, v169
	v_mul_f32_e32 v169, v101, v215
	v_mul_f32_e32 v101, v101, v214
	v_fma_f32 v101, -v97, v215, v101
	v_fma_f32 v97, v97, v214, v169
	v_mul_f32_e32 v169, v102, v217
	v_mul_f32_e32 v102, v102, v216
	v_fma_f32 v102, -v98, v217, v102
	v_fma_f32 v98, v98, v216, v169
	v_mul_f32_e32 v169, v103, v219
	v_mul_f32_e32 v103, v103, v218
	v_fma_f32 v103, -v99, v219, v103
	v_fma_f32 v99, v99, v218, v169
	v_mul_f32_e32 v169, v84, v221
	v_mul_f32_e32 v84, v84, v220
	v_fma_f32 v84, -v80, v221, v84
	v_fma_f32 v80, v80, v220, v169
	v_mul_f32_e32 v169, v85, v223
	v_mul_f32_e32 v85, v85, v222
	v_fma_f32 v85, -v81, v223, v85
	v_fma_f32 v81, v81, v222, v169
	v_mul_f32_e32 v169, v86, v225
	v_mul_f32_e32 v86, v86, v224
	v_fma_f32 v86, -v82, v225, v86
	v_fma_f32 v82, v82, v224, v169
	v_mul_f32_e32 v169, v87, v227
	v_mul_f32_e32 v87, v87, v226
	v_fma_f32 v87, -v83, v227, v87
	v_fma_f32 v83, v83, v226, v169
	v_mul_f32_e32 v169, v68, v229
	v_mul_f32_e32 v68, v68, v228
	v_fma_f32 v68, -v64, v229, v68
	v_fma_f32 v64, v64, v228, v169
	v_mul_f32_e32 v169, v69, v231
	v_mul_f32_e32 v69, v69, v230
	v_fma_f32 v69, -v65, v231, v69
	v_fma_f32 v65, v65, v230, v169
	v_mul_f32_e32 v169, v70, v233
	v_mul_f32_e32 v70, v70, v232
	v_fma_f32 v70, -v66, v233, v70
	v_fma_f32 v66, v66, v232, v169
	v_mul_f32_e32 v169, v71, v235
	v_mul_f32_e32 v71, v71, v234
	v_fma_f32 v71, -v67, v235, v71
	v_fma_f32 v67, v67, v234, v169
	v_mul_f32_e32 v169, v52, v237
	v_mul_f32_e32 v52, v52, v236
	v_fma_f32 v52, -v48, v237, v52
	v_fma_f32 v48, v48, v236, v169
	v_mul_f32_e32 v169, v53, v239
	v_mul_f32_e32 v53, v53, v238
	v_fma_f32 v53, -v49, v239, v53
	v_fma_f32 v49, v49, v238, v169
	v_mul_f32_e32 v169, v54, v241
	v_mul_f32_e32 v54, v54, v240
	v_fma_f32 v54, -v50, v241, v54
	v_fma_f32 v50, v50, v240, v169
	v_mul_f32_e32 v169, v55, v243
	v_mul_f32_e32 v55, v55, v242
	v_fma_f32 v55, -v51, v243, v55
	v_fma_f32 v51, v51, v242, v169
	v_mul_f32_e32 v169, v36, v245
	v_mul_f32_e32 v36, v36, v244
	v_fma_f32 v36, -v32, v245, v36
	v_fma_f32 v32, v32, v244, v169
	v_mul_f32_e32 v169, v37, v247
	v_mul_f32_e32 v37, v37, v246
	v_fma_f32 v37, -v33, v247, v37
	v_fma_f32 v33, v33, v246, v169
	v_mul_f32_e32 v169, v38, v249
	v_mul_f32_e32 v38, v38, v248
	v_fma_f32 v38, -v34, v249, v38
	v_fma_f32 v34, v34, v248, v169
	v_mul_f32_e32 v169, v39, v251
	v_mul_f32_e32 v39, v39, v250
	v_fma_f32 v39, -v35, v251, v39
	v_fma_f32 v35, v35, v250, v169
	v_mul_f32_e32 v169, v20, v179
	v_mul_f32_e32 v20, v20, v178
	v_fma_f32 v20, -v16, v179, v20
	v_fma_f32 v16, v16, v178, v169
	v_mul_f32_e32 v169, v21, v181
	v_mul_f32_e32 v21, v21, v180
	v_fma_f32 v21, -v17, v181, v21
	v_fma_f32 v17, v17, v180, v169
	v_mul_f32_e32 v169, v22, v183
	v_mul_f32_e32 v22, v22, v182
	v_fma_f32 v22, -v18, v183, v22
	v_fma_f32 v18, v18, v182, v169
	v_mul_f32_e32 v169, v23, v185
	v_mul_f32_e32 v23, v23, v184
	v_fma_f32 v23, -v19, v185, v23
	v_fma_f32 v19, v19, v184, v169
	v_mul_f32_e32 v169, v4, v187
	v_mul_f32_e32 v4, v4, v186
	v_fma_f32 v4, -v0, v187, v4
	v_fma_f32 v0, v0, v186, v169
	v_mul_f32_e32 v169, v5, v189
	v_mul_f32_e32 v5, v5, v188
	v_fma_f32 v5, -v1, v189, v5
	v_fma_f32 v1, v1, v188, v169
	v_mul_f32_e32 v169, v6, v191
	v_mul_f32_e32 v6, v6, v190
	v_fma_f32 v6, -v2, v191, v6
	v_fma_f32 v2, v2, v190, v169
	v_mul_f32_e32 v169, v7, v193
	v_mul_f32_e32 v7, v7, v192
	v_fma_f32 v7, -v3, v193, v7
	v_fma_f32 v3, v3, v192, v169

; DI void rope4(f32x4& v0, f32x4& v1, const float* tab  ) {
;     const f32x4 t0 = *(const f32x4*)tab, t1 = *(const f32x4*)(tab + 4);
;     const float c[4] = {t0[0], t0[2], t1[0], t1[2]}, s[4] = {t0[1], t0[3], t1[1], t1[3]};
; #pragma unroll
;     for (int j = 0; j < 4; ++j) { const float a = v0[j], b = v1[j]; v0[j] = a * c[j] - b * s[j]; v1[j] = b * c[j] + a * s[j]; }
; }
;     DI void operator()(const f32x4 (&acc)[2][2][4][2], const Unit& u, int wr, int wc, int fr, int fq) const {
;     ...
;                     } else if (colg >= C_KPE && colg < C_RQ) {
;                         if (lat) rope4(v0, v1, (const float*)(ws + WS_TABM) + ((size_t)t * 32 + ((colg - C_KPE) >> 5) * 16 + 4 * fq) * 2);
.Lip0_k1_kpe:
	s_cmp_eq_u32 s27, 0
	s_cbranch_scc1 .Lip0_nr1k
	s_sub_u32 s97, s35, 0xd00
	s_and_b32 s97, s97, 0x7f
	s_lshr_b32 s97, s97, 5
	s_lshl_b32 s97, s97, 7
	s_sub_u32 s93, s27, 1
	s_lshl_b32 s93, s93, 16
	s_add_u32 s93, s93, s97
	v_lshlrev_b32_e32 v169, 5, v196
	v_lshl_add_u32 v158, v195, 8, v169
	v_add_u32_e32 v158, s93, v158
	v_add_u32_e32 v159, 0x1000, v158
	v_add_u32_e32 v160, 0x2000, v158
	v_add_u32_e32 v161, 0x3000, v158
	v_add_u32_e32 v162, 0x8000, v158
	v_add_u32_e32 v163, 0x9000, v158
	v_add_u32_e32 v164, 0xa000, v158
	v_add_u32_e32 v165, 0xb000, v158
	s_add_u32 s10, s50, 0x80000
	s_addc_u32 s11, s51, 0
	global_load_dwordx4 v[204:207], v158, s[10:11]
	global_load_dwordx4 v[208:211], v158, s[10:11] offset:16
	global_load_dwordx4 v[212:215], v159, s[10:11]
	global_load_dwordx4 v[216:219], v159, s[10:11] offset:16
	global_load_dwordx4 v[220:223], v160, s[10:11]
	global_load_dwordx4 v[224:227], v160, s[10:11] offset:16
	global_load_dwordx4 v[228:231], v161, s[10:11]
	global_load_dwordx4 v[232:235], v161, s[10:11] offset:16
	global_load_dwordx4 v[236:239], v162, s[10:11]
	global_load_dwordx4 v[240:243], v162, s[10:11] offset:16
	global_load_dwordx4 v[244:247], v163, s[10:11]
	global_load_dwordx4 v[248:251], v163, s[10:11] offset:16
	global_load_dwordx4 v[178:181], v164, s[10:11]
	global_load_dwordx4 v[182:185], v164, s[10:11] offset:16
	global_load_dwordx4 v[186:189], v165, s[10:11]
	global_load_dwordx4 v[190:193], v165, s[10:11] offset:16
	s_waitcnt vmcnt(0)
	v_mul_f32_e32 v169, v116, v205
	v_mul_f32_e32 v116, v116, v204
	v_fma_f32 v116, -v112, v205, v116
	v_fma_f32 v112, v112, v204, v169
	v_mul_f32_e32 v169, v117, v207
	v_mul_f32_e32 v117, v117, v206
	v_fma_f32 v117, -v113, v207, v117
	v_fma_f32 v113, v113, v206, v169
	v_mul_f32_e32 v169, v118, v209
	v_mul_f32_e32 v118, v118, v208
	v_fma_f32 v118, -v114, v209, v118
	v_fma_f32 v114, v114, v208, v169
	v_mul_f32_e32 v169, v119, v211
	v_mul_f32_e32 v119, v119, v210
	v_fma_f32 v119, -v115, v211, v119
	v_fma_f32 v115, v115, v210, v169
	v_mul_f32_e32 v169, v100, v213
	v_mul_f32_e32 v100, v100, v212
	v_fma_f32 v100, -v96, v213, v100
	v_fma_f32 v96, v96, v212, v169
	v_mul_f32_e32 v169, v101, v215
	v_mul_f32_e32 v101, v101, v214
	v_fma_f32 v101, -v97, v215, v101
	v_fma_f32 v97, v97, v214, v169
	v_mul_f32_e32 v169, v102, v217
	v_mul_f32_e32 v102, v102, v216
	v_fma_f32 v102, -v98, v217, v102
	v_fma_f32 v98, v98, v216, v169
	v_mul_f32_e32 v169, v103, v219
	v_mul_f32_e32 v103, v103, v218
	v_fma_f32 v103, -v99, v219, v103
	v_fma_f32 v99, v99, v218, v169
	v_mul_f32_e32 v169, v84, v221
	v_mul_f32_e32 v84, v84, v220
	v_fma_f32 v84, -v80, v221, v84
	v_fma_f32 v80, v80, v220, v169
	v_mul_f32_e32 v169, v85, v223
	v_mul_f32_e32 v85, v85, v222
	v_fma_f32 v85, -v81, v223, v85
	v_fma_f32 v81, v81, v222, v169
	v_mul_f32_e32 v169, v86, v225
	v_mul_f32_e32 v86, v86, v224
	v_fma_f32 v86, -v82, v225, v86
	v_fma_f32 v82, v82, v224, v169
	v_mul_f32_e32 v169, v87, v227
	v_mul_f32_e32 v87, v87, v226
	v_fma_f32 v87, -v83, v227, v87
	v_fma_f32 v83, v83, v226, v169
	v_mul_f32_e32 v169, v68, v229
	v_mul_f32_e32 v68, v68, v228
	v_fma_f32 v68, -v64, v229, v68
	v_fma_f32 v64, v64, v228, v169
	v_mul_f32_e32 v169, v69, v231
	v_mul_f32_e32 v69, v69, v230
	v_fma_f32 v69, -v65, v231, v69
	v_fma_f32 v65, v65, v230, v169
	v_mul_f32_e32 v169, v70, v233
	v_mul_f32_e32 v70, v70, v232
	v_fma_f32 v70, -v66, v233, v70
	v_fma_f32 v66, v66, v232, v169
	v_mul_f32_e32 v169, v71, v235
	v_mul_f32_e32 v71, v71, v234
	v_fma_f32 v71, -v67, v235, v71
	v_fma_f32 v67, v67, v234, v169
	v_mul_f32_e32 v169, v52, v237
	v_mul_f32_e32 v52, v52, v236
	v_fma_f32 v52, -v48, v237, v52
	v_fma_f32 v48, v48, v236, v169
	v_mul_f32_e32 v169, v53, v239
	v_mul_f32_e32 v53, v53, v238
	v_fma_f32 v53, -v49, v239, v53
	v_fma_f32 v49, v49, v238, v169
	v_mul_f32_e32 v169, v54, v241
	v_mul_f32_e32 v54, v54, v240
	v_fma_f32 v54, -v50, v241, v54
	v_fma_f32 v50, v50, v240, v169
	v_mul_f32_e32 v169, v55, v243
	v_mul_f32_e32 v55, v55, v242
	v_fma_f32 v55, -v51, v243, v55
	v_fma_f32 v51, v51, v242, v169
	v_mul_f32_e32 v169, v36, v245
	v_mul_f32_e32 v36, v36, v244
	v_fma_f32 v36, -v32, v245, v36
	v_fma_f32 v32, v32, v244, v169
	v_mul_f32_e32 v169, v37, v247
	v_mul_f32_e32 v37, v37, v246
	v_fma_f32 v37, -v33, v247, v37
	v_fma_f32 v33, v33, v246, v169
	v_mul_f32_e32 v169, v38, v249
	v_mul_f32_e32 v38, v38, v248
	v_fma_f32 v38, -v34, v249, v38
	v_fma_f32 v34, v34, v248, v169
	v_mul_f32_e32 v169, v39, v251
	v_mul_f32_e32 v39, v39, v250
	v_fma_f32 v39, -v35, v251, v39
	v_fma_f32 v35, v35, v250, v169
	v_mul_f32_e32 v169, v20, v179
	v_mul_f32_e32 v20, v20, v178
	v_fma_f32 v20, -v16, v179, v20
	v_fma_f32 v16, v16, v178, v169
	v_mul_f32_e32 v169, v21, v181
	v_mul_f32_e32 v21, v21, v180
	v_fma_f32 v21, -v17, v181, v21
	v_fma_f32 v17, v17, v180, v169
	v_mul_f32_e32 v169, v22, v183
	v_mul_f32_e32 v22, v22, v182
	v_fma_f32 v22, -v18, v183, v22
	v_fma_f32 v18, v18, v182, v169
	v_mul_f32_e32 v169, v23, v185
	v_mul_f32_e32 v23, v23, v184
	v_fma_f32 v23, -v19, v185, v23
	v_fma_f32 v19, v19, v184, v169
	v_mul_f32_e32 v169, v4, v187
	v_mul_f32_e32 v4, v4, v186
	v_fma_f32 v4, -v0, v187, v4
	v_fma_f32 v0, v0, v186, v169
	v_mul_f32_e32 v169, v5, v189
	v_mul_f32_e32 v5, v5, v188
	v_fma_f32 v5, -v1, v189, v5
	v_fma_f32 v1, v1, v188, v169
	v_mul_f32_e32 v169, v6, v191
	v_mul_f32_e32 v6, v6, v190
	v_fma_f32 v6, -v2, v191, v6
	v_fma_f32 v2, v2, v190, v169
	v_mul_f32_e32 v169, v7, v193
	v_mul_f32_e32 v7, v7, v192
	v_fma_f32 v7, -v3, v193, v7
	v_fma_f32 v3, v3, v192, v169
; DI void st_bf16x4(bf16_t* p, f32x4 v) { u32x2 w; w.x = cvt_pk_bf16(v[0], v[1]); w.y = cvt_pk_bf16(v[2], v[3]); *(u32x2*)p = w; }
;     DI void operator()(const f32x4 (&acc)[2][2][4][2], const Unit& u, int wr, int wc, int fr, int fq) const {
;     ...
;                     } else if (colg >= C_KPE && colg < C_RQ) {
;                         if (lat) rope4(v0, v1, (const float*)(ws + WS_TABM) + ((size_t)t * 32 + ((colg - C_KPE) >> 5) * 16 + 4 * fq) * 2);
;                         bf16_t* kp = (bf16_t*)(ws + WS_KPE) + (size_t)row * 64 + (c0 - C_KPE);
;                         st_bf16x4(kp, v0); st_bf16x4(kp + 16, v1);
.Lip0_nr1k:
	s_lshl_b32 s93, s8, 15
	s_add_u32 s10, s50, 0x1cb00000
	s_addc_u32 s11, s51, 0
	s_add_u32 s10, s10, s93
	s_addc_u32 s11, s11, 0
	s_sub_u32 s93, s35, 0xd00
	s_lshl_b32 s93, s93, 1
	s_add_u32 s10, s10, s93
	s_addc_u32 s11, s11, 0
	v_lshlrev_b32_e32 v158, 7, v195
	v_lshl_add_u32 v158, v196, 3, v158
	v_add_u32_e32 v159, 0x800, v158
	v_add_u32_e32 v160, 0x1000, v158
	v_add_u32_e32 v161, 0x1800, v158
	v_add_u32_e32 v162, 0x4000, v158
	v_add_u32_e32 v163, 0x4800, v158
	v_add_u32_e32 v164, 0x5000, v158
	v_add_u32_e32 v165, 0x5800, v158
	v_cvt_pk_bf16_f32 v116, v116, v117
	v_cvt_pk_bf16_f32 v117, v118, v119
	global_store_dwordx2 v158, v[116:117], s[10:11] offset:0
	v_cvt_pk_bf16_f32 v112, v112, v113
	v_cvt_pk_bf16_f32 v113, v114, v115
	global_store_dwordx2 v158, v[112:113], s[10:11] offset:32
	v_cvt_pk_bf16_f32 v100, v100, v101
	v_cvt_pk_bf16_f32 v101, v102, v103
	global_store_dwordx2 v159, v[100:101], s[10:11] offset:0
	v_cvt_pk_bf16_f32 v96, v96, v97
	v_cvt_pk_bf16_f32 v97, v98, v99
	global_store_dwordx2 v159, v[96:97], s[10:11] offset:32
	v_cvt_pk_bf16_f32 v84, v84, v85
	v_cvt_pk_bf16_f32 v85, v86, v87
	global_store_dwordx2 v160, v[84:85], s[10:11] offset:0
	v_cvt_pk_bf16_f32 v80, v80, v81
	v_cvt_pk_bf16_f32 v81, v82, v83
	global_store_dwordx2 v160, v[80:81], s[10:11] offset:32
	v_cvt_pk_bf16_f32 v68, v68, v69
	v_cvt_pk_bf16_f32 v69, v70, v71
	global_store_dwordx2 v161, v[68:69], s[10:11] offset:0
	v_cvt_pk_bf16_f32 v64, v64, v65
	v_cvt_pk_bf16_f32 v65, v66, v67
	global_store_dwordx2 v161, v[64:65], s[10:11] offset:32
	v_cvt_pk_bf16_f32 v52, v52, v53
	v_cvt_pk_bf16_f32 v53, v54, v55
	global_store_dwordx2 v162, v[52:53], s[10:11] offset:0
	v_cvt_pk_bf16_f32 v48, v48, v49
	v_cvt_pk_bf16_f32 v49, v50, v51
	global_store_dwordx2 v162, v[48:49], s[10:11] offset:32
	v_cvt_pk_bf16_f32 v36, v36, v37
	v_cvt_pk_bf16_f32 v37, v38, v39
	global_store_dwordx2 v163, v[36:37], s[10:11] offset:0
	v_cvt_pk_bf16_f32 v32, v32, v33
	v_cvt_pk_bf16_f32 v33, v34, v35
	global_store_dwordx2 v163, v[32:33], s[10:11] offset:32
	v_cvt_pk_bf16_f32 v20, v20, v21
	v_cvt_pk_bf16_f32 v21, v22, v23
	global_store_dwordx2 v164, v[20:21], s[10:11] offset:0
	v_cvt_pk_bf16_f32 v16, v16, v17
	v_cvt_pk_bf16_f32 v17, v18, v19
	global_store_dwordx2 v164, v[16:17], s[10:11] offset:32
	v_cvt_pk_bf16_f32 v4, v4, v5
	v_cvt_pk_bf16_f32 v5, v6, v7
	global_store_dwordx2 v165, v[4:5], s[10:11] offset:0
	v_cvt_pk_bf16_f32 v0, v0, v1
	v_cvt_pk_bf16_f32 v1, v2, v3
	global_store_dwordx2 v165, v[0:1], s[10:11] offset:32
	s_branch .Lip0_k1_end

; #define G_STAGE(bufoff, gbase, voff) do { _Pragma("unroll") for (int _i = 0; _i < 2; ++_i) \
;         __builtin_amdgcn_global_load_lds((const unsigned*)((const char*)(gbase) + (voff)[_i]), (LAS unsigned*)(lds + (bufoff) + ldsw + _i * 8192), 16, 0, 0); } while (0)
; #define G_LDA(dst, b, h) do { _Pragma("unroll") for (int m = 0; m < 4; ++m) _Pragma("unroll") for (int k = 0; k < 2; ++k) dst[m][k] = *(const LAS bf16x8*)(lds + G_SA(b, h) + aoff + m * 2048 + k * 1024); } while (0)
; #define G_LDB(dst, b, h) do { _Pragma("unroll") for (int n = 0; n < 2; ++n) _Pragma("unroll") for (int k = 0; k < 2; ++k) dst[n][k] = *(const LAS bf16x8*)(lds + G_SB(b, h) + boff + n * 2048 + k * 1024); } while (0)
; #define G_MMA(ai, bj, At, Bt_) do { __builtin_amdgcn_s_setprio(1); _Pragma("unroll") for (int m = 0; m < 4; ++m) _Pragma("unroll") for (int n = 0; n < 2; ++n) _Pragma("unroll") for (int k = 0; k < 2; ++k) \
;         acc[ai][bj][m][n] = __builtin_amdgcn_mfma_f32_16x16x32_bf16(Bt_[n][k], At[m][k], acc[ai][bj][m][n], 0, 0, 0); __builtin_amdgcn_s_setprio(0); } while (0)
; #define G_WAIT_V(n) asm volatile("s_waitcnt vmcnt(" #n ")" ::: "memory")
; #define G_WAIT_L(n) asm volatile("s_waitcnt lgkmcnt(" #n ")" ::: "memory")
; #define G_BAR __builtin_amdgcn_s_barrier()
; #define G_SCHED __builtin_amdgcn_sched_barrier(0)
; template <class Epi, bool PERMROWS = false>
; DI void gemm_phase(LAS unsigned char* lds, const bf16_t* A, int lda, const bf16_t* Bt, int K, const Sched& S, const Epi& E) {
;     ...
;             G_LDB(B0, 0, 0); G_SCHED; G_LDA(At, 0, 0); G_STAGE(G_SA(1, 1), a1 + hstepA, voffA);
;             G_WAIT_L(8); G_BAR; G_WAIT_L(0); G_MMA(0, 0, At, B0); G_BAR; G_SCHED;
;             G_LDB(B1, 0, 1); G_STAGE(G_SB(0, 0), b2, voffB);
;             G_BAR; G_WAIT_L(0); G_MMA(0, 1, At, B1); G_BAR;
;             G_LDA(At, 0, 1); G_STAGE(G_SA(0, 0), a2, voffA);
;             G_BAR; G_WAIT_L(0); G_MMA(1, 0, At, B0); G_BAR; G_SCHED;
;             G_STAGE(G_SB(0, 1), b2 + hstepB, voffB);
;             G_WAIT_V(6); G_BAR; G_MMA(1, 1, At, B1); G_BAR;
.LBB0_1981:
	s_waitcnt lgkmcnt(0)
	ds_read_b128 v[150:153], v174
	ds_read_b128 v[154:157], v174 offset:1024
	ds_read_b128 v[158:161], v174 offset:2048
	ds_read_b128 v[162:165], v174 offset:3072
	s_add_u32 s14, s12, 0xfff80080
	s_addc_u32 s15, s13, -1
	s_cmp_eq_u32 s43, 28
	s_cselect_b32 s77, s11, s15
	s_cselect_b32 s76, s20, s14
	s_cselect_b32 s15, s21, s42
	s_cselect_b32 s14, s22, s27
	v_lshl_add_u64 v[208:209], s[12:13], 0, v[144:145]
	s_add_i32 m0, s86, 0xc000
	ds_read_b128 v[166:169], v175
	ds_read_b128 v[178:181], v175 offset:1024
	ds_read_b128 v[182:185], v175 offset:2048
	ds_read_b128 v[186:189], v175 offset:3072
	ds_read_b128 v[190:193], v175 offset:4096
	ds_read_b128 v[194:197], v175 offset:5120
	ds_read_b128 v[198:201], v175 offset:6144
	ds_read_b128 v[204:207], v175 offset:7168
	global_load_lds_dwordx4 v[208:209], off
	v_lshl_add_u64 v[208:209], s[12:13], 0, v[142:143]
	s_add_i32 m0, s86, 0xe000
	s_nop 0
	global_load_lds_dwordx4 v[208:209], off
	s_waitcnt lgkmcnt(8)
	s_barrier
	s_waitcnt lgkmcnt(0)
	s_setprio 1
	s_waitcnt lgkmcnt(0)
	v_mfma_f32_16x16x32_bf16 v[124:127], v[150:153], v[166:169], v[124:127]
	v_mfma_f32_16x16x32_bf16 v[120:123], v[158:161], v[166:169], v[120:123]
	v_mfma_f32_16x16x32_bf16 v[108:111], v[150:153], v[182:185], v[108:111]
	v_mfma_f32_16x16x32_bf16 v[104:107], v[158:161], v[182:185], v[104:107]
	v_mfma_f32_16x16x32_bf16 v[92:95], v[150:153], v[190:193], v[92:95]
	v_mfma_f32_16x16x32_bf16 v[88:91], v[158:161], v[190:193], v[88:91]
	v_mfma_f32_16x16x32_bf16 v[76:79], v[150:153], v[198:201], v[76:79]
	v_mfma_f32_16x16x32_bf16 v[72:75], v[158:161], v[198:201], v[72:75]
	v_mfma_f32_16x16x32_bf16 v[124:127], v[154:157], v[178:181], v[124:127]
	v_mfma_f32_16x16x32_bf16 v[120:123], v[162:165], v[178:181], v[120:123]
	v_mfma_f32_16x16x32_bf16 v[108:111], v[154:157], v[186:189], v[108:111]
	v_mfma_f32_16x16x32_bf16 v[104:107], v[162:165], v[186:189], v[104:107]
	v_mfma_f32_16x16x32_bf16 v[92:95], v[154:157], v[194:197], v[92:95]
	v_mfma_f32_16x16x32_bf16 v[88:91], v[162:165], v[194:197], v[88:91]
	v_mfma_f32_16x16x32_bf16 v[76:79], v[154:157], v[204:207], v[76:79]
	v_mfma_f32_16x16x32_bf16 v[72:75], v[162:165], v[204:207], v[72:75]
	s_setprio 0
	s_barrier
	s_add_i32 s28, s6, s83
	v_lshl_add_u64 v[224:225], s[14:15], 0, v[128:129]
	s_mov_b32 m0, s28
	ds_read_b128 v[208:211], v176
	ds_read_b128 v[212:215], v176 offset:1024
	ds_read_b128 v[216:219], v176 offset:2048
	ds_read_b128 v[220:223], v176 offset:3072
	global_load_lds_dwordx4 v[224:225], off
	v_lshl_add_u64 v[226:227], s[14:15], 0, v[130:131]
	s_add_i32 m0, s28, 0x2000
	s_nop 0
	global_load_lds_dwordx4 v[226:227], off
	s_barrier
	s_waitcnt lgkmcnt(0)
	s_setprio 1
	s_waitcnt lgkmcnt(0)
	v_mfma_f32_16x16x32_bf16 v[116:119], v[208:211], v[166:169], v[116:119]
	v_mfma_f32_16x16x32_bf16 v[112:115], v[216:219], v[166:169], v[112:115]
	v_mfma_f32_16x16x32_bf16 v[100:103], v[208:211], v[182:185], v[100:103]
	v_mfma_f32_16x16x32_bf16 v[96:99], v[216:219], v[182:185], v[96:99]
	v_mfma_f32_16x16x32_bf16 v[84:87], v[208:211], v[190:193], v[84:87]
	v_mfma_f32_16x16x32_bf16 v[80:83], v[216:219], v[190:193], v[80:83]
	v_mfma_f32_16x16x32_bf16 v[68:71], v[208:211], v[198:201], v[68:71]
	v_mfma_f32_16x16x32_bf16 v[64:67], v[216:219], v[198:201], v[64:67]
	v_mfma_f32_16x16x32_bf16 v[116:119], v[212:215], v[178:181], v[116:119]
	v_mfma_f32_16x16x32_bf16 v[112:115], v[220:223], v[178:181], v[112:115]
	v_mfma_f32_16x16x32_bf16 v[100:103], v[212:215], v[186:189], v[100:103]
	v_mfma_f32_16x16x32_bf16 v[96:99], v[220:223], v[186:189], v[96:99]
	v_mfma_f32_16x16x32_bf16 v[84:87], v[212:215], v[194:197], v[84:87]
	v_mfma_f32_16x16x32_bf16 v[80:83], v[220:223], v[194:197], v[80:83]
	v_mfma_f32_16x16x32_bf16 v[68:71], v[212:215], v[204:207], v[68:71]
	v_mfma_f32_16x16x32_bf16 v[64:67], v[220:223], v[204:207], v[64:67]
	s_setprio 0
	s_mov_b32 m0, s86
	v_lshl_add_u64 v[228:229], s[76:77], 0, v[128:129]
	s_barrier
	ds_read_b128 v[166:169], v175 offset:16384
	ds_read_b128 v[178:181], v175 offset:17408
	ds_read_b128 v[182:185], v175 offset:18432
	ds_read_b128 v[186:189], v175 offset:19456
	ds_read_b128 v[190:193], v175 offset:20480
	ds_read_b128 v[194:197], v175 offset:21504
	ds_read_b128 v[198:201], v175 offset:22528
	ds_read_b128 v[204:207], v175 offset:23552
	global_load_lds_dwordx4 v[228:229], off
	v_lshl_add_u64 v[230:231], s[76:77], 0, v[130:131]
	s_mov_b32 m0, s87
	s_nop 0
	global_load_lds_dwordx4 v[230:231], off
	s_barrier
	s_waitcnt lgkmcnt(0)
	s_setprio 1
	s_waitcnt lgkmcnt(0)
	v_mfma_f32_16x16x32_bf16 v[60:63], v[150:153], v[166:169], v[60:63]
	v_mfma_f32_16x16x32_bf16 v[56:59], v[158:161], v[166:169], v[56:59]
	v_mfma_f32_16x16x32_bf16 v[44:47], v[150:153], v[182:185], v[44:47]
	v_mfma_f32_16x16x32_bf16 v[40:43], v[158:161], v[182:185], v[40:43]
	v_mfma_f32_16x16x32_bf16 v[28:31], v[150:153], v[190:193], v[28:31]
	v_mfma_f32_16x16x32_bf16 v[24:27], v[158:161], v[190:193], v[24:27]
	v_mfma_f32_16x16x32_bf16 v[12:15], v[150:153], v[198:201], v[12:15]
	v_mfma_f32_16x16x32_bf16 v[8:11], v[158:161], v[198:201], v[8:11]
	v_mfma_f32_16x16x32_bf16 v[60:63], v[154:157], v[178:181], v[60:63]
	v_mfma_f32_16x16x32_bf16 v[56:59], v[162:165], v[178:181], v[56:59]
	v_mfma_f32_16x16x32_bf16 v[44:47], v[154:157], v[186:189], v[44:47]
	v_mfma_f32_16x16x32_bf16 v[40:43], v[162:165], v[186:189], v[40:43]
	v_mfma_f32_16x16x32_bf16 v[28:31], v[154:157], v[194:197], v[28:31]
	v_mfma_f32_16x16x32_bf16 v[24:27], v[162:165], v[194:197], v[24:27]
	v_mfma_f32_16x16x32_bf16 v[12:15], v[154:157], v[204:207], v[12:15]
	v_mfma_f32_16x16x32_bf16 v[8:11], v[162:165], v[204:207], v[8:11]
	s_setprio 0
	s_barrier
; #define G_STAGE(bufoff, gbase, voff) do { _Pragma("unroll") for (int _i = 0; _i < 2; ++_i) \
;         __builtin_amdgcn_global_load_lds((const unsigned*)((const char*)(gbase) + (voff)[_i]), (LAS unsigned*)(lds + (bufoff) + ldsw + _i * 8192), 16, 0, 0); } while (0)
; #define G_LDA(dst, b, h) do { _Pragma("unroll") for (int m = 0; m < 4; ++m) _Pragma("unroll") for (int k = 0; k < 2; ++k) dst[m][k] = *(const LAS bf16x8*)(lds + G_SA(b, h) + aoff + m * 2048 + k * 1024); } while (0)
; #define G_LDB(dst, b, h) do { _Pragma("unroll") for (int n = 0; n < 2; ++n) _Pragma("unroll") for (int k = 0; k < 2; ++k) dst[n][k] = *(const LAS bf16x8*)(lds + G_SB(b, h) + boff + n * 2048 + k * 1024); } while (0)
; #define G_MMA(ai, bj, At, Bt_) do { __builtin_amdgcn_s_setprio(1); _Pragma("unroll") for (int m = 0; m < 4; ++m) _Pragma("unroll") for (int n = 0; n < 2; ++n) _Pragma("unroll") for (int k = 0; k < 2; ++k) \
;         acc[ai][bj][m][n] = __builtin_amdgcn_mfma_f32_16x16x32_bf16(Bt_[n][k], At[m][k], acc[ai][bj][m][n], 0, 0, 0); __builtin_amdgcn_s_setprio(0); } while (0)
; #define G_WAIT_V(n) asm volatile("s_waitcnt vmcnt(" #n ")" ::: "memory")
; #define G_WAIT_L(n) asm volatile("s_waitcnt lgkmcnt(" #n ")" ::: "memory")
; #define G_BAR __builtin_amdgcn_s_barrier()
; #define G_SCHED __builtin_amdgcn_sched_barrier(0)
; template <class Epi, bool PERMROWS = false>
; DI void gemm_phase(LAS unsigned char* lds, const bf16_t* A, int lda, const bf16_t* Bt, int K, const Sched& S, const Epi& E) {
;     ...
;             G_WAIT_V(6); G_BAR; G_MMA(1, 1, At, B1); G_BAR;
;             G_LDB(B0, 1, 0); G_SCHED; G_LDA(At, 1, 0); G_STAGE(G_SA(0, 1), a2 + hstepA, voffA);
;             G_WAIT_L(8); G_BAR; G_WAIT_L(0); G_MMA(0, 0, At, B0); G_BAR; G_SCHED;
;             G_LDB(B1, 1, 1); G_STAGE(G_SB(1, 0), b3, voffB);
;             G_BAR; G_WAIT_L(0); G_MMA(0, 1, At, B1); G_BAR;
;             G_LDA(At, 1, 1); G_STAGE(G_SA(1, 0), a3, voffA);
;             G_BAR; G_WAIT_L(0); G_MMA(1, 0, At, B0); G_BAR; G_SCHED;
	s_add_u32 s28, s14, 0x80000
	s_addc_u32 s29, s15, 0
	s_add_i32 s54, s7, s83
	v_lshl_add_u64 v[150:151], s[28:29], 0, v[128:129]
	s_mov_b32 m0, s54
	s_nop 0
	global_load_lds_dwordx4 v[150:151], off
	v_lshl_add_u64 v[150:151], s[28:29], 0, v[130:131]
	s_add_i32 m0, s54, 0x2000
	s_nop 0
	global_load_lds_dwordx4 v[150:151], off
	s_waitcnt vmcnt(6)
	s_barrier
	s_setprio 1
	v_mfma_f32_16x16x32_bf16 v[52:55], v[208:211], v[166:169], v[52:55]
	v_mfma_f32_16x16x32_bf16 v[48:51], v[216:219], v[166:169], v[48:51]
	v_mfma_f32_16x16x32_bf16 v[36:39], v[208:211], v[182:185], v[36:39]
	v_mfma_f32_16x16x32_bf16 v[32:35], v[216:219], v[182:185], v[32:35]
	v_mfma_f32_16x16x32_bf16 v[20:23], v[208:211], v[190:193], v[20:23]
	v_mfma_f32_16x16x32_bf16 v[16:19], v[216:219], v[190:193], v[16:19]
	v_mfma_f32_16x16x32_bf16 v[4:7], v[208:211], v[198:201], v[4:7]
	v_mfma_f32_16x16x32_bf16 v[0:3], v[216:219], v[198:201], v[0:3]
	v_mfma_f32_16x16x32_bf16 v[52:55], v[212:215], v[178:181], v[52:55]
	v_mfma_f32_16x16x32_bf16 v[48:51], v[220:223], v[178:181], v[48:51]
	v_mfma_f32_16x16x32_bf16 v[36:39], v[212:215], v[186:189], v[36:39]
	v_mfma_f32_16x16x32_bf16 v[32:35], v[220:223], v[186:189], v[32:35]
	v_mfma_f32_16x16x32_bf16 v[20:23], v[212:215], v[194:197], v[20:23]
	v_mfma_f32_16x16x32_bf16 v[16:19], v[220:223], v[194:197], v[16:19]
	v_mfma_f32_16x16x32_bf16 v[4:7], v[212:215], v[204:207], v[4:7]
	v_mfma_f32_16x16x32_bf16 v[0:3], v[220:223], v[204:207], v[0:3]
	s_setprio 0
	s_add_i32 s54, 0, 0x18000
	v_add_u32_e32 v132, s54, v170
	s_barrier
	ds_read_b128 v[150:153], v132
	ds_read_b128 v[154:157], v132 offset:1024
	ds_read_b128 v[158:161], v132 offset:2048
	ds_read_b128 v[162:165], v132 offset:3072
	s_add_u32 s28, s76, 0x80000
	s_addc_u32 s29, s77, 0
	s_mov_b32 m0, s94
	v_lshl_add_u64 v[208:209], s[28:29], 0, v[128:129]
	ds_read_b128 v[166:169], v175 offset:32768
	ds_read_b128 v[178:181], v175 offset:33792
	ds_read_b128 v[182:185], v175 offset:34816
	ds_read_b128 v[186:189], v175 offset:35840
	ds_read_b128 v[190:193], v175 offset:36864
	ds_read_b128 v[194:197], v175 offset:37888
	ds_read_b128 v[198:201], v175 offset:38912
	ds_read_b128 v[204:207], v175 offset:39936
	global_load_lds_dwordx4 v[208:209], off
	v_lshl_add_u64 v[208:209], s[28:29], 0, v[130:131]
	s_mov_b32 m0, s95
	s_nop 0
	global_load_lds_dwordx4 v[208:209], off
	s_waitcnt lgkmcnt(8)
	s_barrier
	s_waitcnt lgkmcnt(0)
	s_setprio 1
	s_waitcnt lgkmcnt(0)
	v_mfma_f32_16x16x32_bf16 v[124:127], v[150:153], v[166:169], v[124:127]
	v_mfma_f32_16x16x32_bf16 v[120:123], v[158:161], v[166:169], v[120:123]
	v_mfma_f32_16x16x32_bf16 v[108:111], v[150:153], v[182:185], v[108:111]
	v_mfma_f32_16x16x32_bf16 v[104:107], v[158:161], v[182:185], v[104:107]
	v_mfma_f32_16x16x32_bf16 v[92:95], v[150:153], v[190:193], v[92:95]
	v_mfma_f32_16x16x32_bf16 v[88:91], v[158:161], v[190:193], v[88:91]
	v_mfma_f32_16x16x32_bf16 v[76:79], v[150:153], v[198:201], v[76:79]
	v_mfma_f32_16x16x32_bf16 v[72:75], v[158:161], v[198:201], v[72:75]
	v_mfma_f32_16x16x32_bf16 v[124:127], v[154:157], v[178:181], v[124:127]
	v_mfma_f32_16x16x32_bf16 v[120:123], v[162:165], v[178:181], v[120:123]
	v_mfma_f32_16x16x32_bf16 v[108:111], v[154:157], v[186:189], v[108:111]
	v_mfma_f32_16x16x32_bf16 v[104:107], v[162:165], v[186:189], v[104:107]
	v_mfma_f32_16x16x32_bf16 v[92:95], v[154:157], v[194:197], v[92:95]
	v_mfma_f32_16x16x32_bf16 v[88:91], v[162:165], v[194:197], v[88:91]
	v_mfma_f32_16x16x32_bf16 v[76:79], v[154:157], v[204:207], v[76:79]
	v_mfma_f32_16x16x32_bf16 v[72:75], v[162:165], v[204:207], v[72:75]
	s_setprio 0
	s_barrier
	s_add_i32 s28, 0, 0x1c000
	s_add_i32 s29, s54, s83
	v_add_u32_e32 v132, s28, v170
	v_lshl_add_u64 v[224:225], v[224:225], 0, s[16:17]
	s_mov_b32 m0, s29
	ds_read_b128 v[208:211], v132
	ds_read_b128 v[212:215], v132 offset:1024
	ds_read_b128 v[216:219], v132 offset:2048
	ds_read_b128 v[220:223], v132 offset:3072
	global_load_lds_dwordx4 v[224:225], off
	v_lshl_add_u64 v[224:225], v[226:227], 0, s[16:17]
	s_add_i32 m0, s29, 0x2000
	s_nop 0
	global_load_lds_dwordx4 v[224:225], off
	s_barrier
	s_waitcnt lgkmcnt(0)
	s_setprio 1
	s_waitcnt lgkmcnt(0)
	v_mfma_f32_16x16x32_bf16 v[116:119], v[208:211], v[166:169], v[116:119]
	v_mfma_f32_16x16x32_bf16 v[112:115], v[216:219], v[166:169], v[112:115]
	v_mfma_f32_16x16x32_bf16 v[100:103], v[208:211], v[182:185], v[100:103]
	v_mfma_f32_16x16x32_bf16 v[96:99], v[216:219], v[182:185], v[96:99]
	v_mfma_f32_16x16x32_bf16 v[84:87], v[208:211], v[190:193], v[84:87]
	v_mfma_f32_16x16x32_bf16 v[80:83], v[216:219], v[190:193], v[80:83]
	v_mfma_f32_16x16x32_bf16 v[68:71], v[208:211], v[198:201], v[68:71]
	v_mfma_f32_16x16x32_bf16 v[64:67], v[216:219], v[198:201], v[64:67]
	v_mfma_f32_16x16x32_bf16 v[116:119], v[212:215], v[178:181], v[116:119]
	v_mfma_f32_16x16x32_bf16 v[112:115], v[220:223], v[178:181], v[112:115]
	v_mfma_f32_16x16x32_bf16 v[100:103], v[212:215], v[186:189], v[100:103]
	v_mfma_f32_16x16x32_bf16 v[96:99], v[220:223], v[186:189], v[96:99]
	v_mfma_f32_16x16x32_bf16 v[84:87], v[212:215], v[194:197], v[84:87]
	v_mfma_f32_16x16x32_bf16 v[80:83], v[220:223], v[194:197], v[80:83]
	v_mfma_f32_16x16x32_bf16 v[68:71], v[212:215], v[204:207], v[68:71]
	v_mfma_f32_16x16x32_bf16 v[64:67], v[220:223], v[204:207], v[64:67]
	s_setprio 0
	s_mov_b32 m0, s97
	v_lshl_add_u64 v[224:225], v[228:229], 0, s[16:17]
	s_barrier
	ds_read_b128 v[166:169], v175 offset:49152
	ds_read_b128 v[178:181], v175 offset:50176
	ds_read_b128 v[182:185], v175 offset:51200
	ds_read_b128 v[186:189], v175 offset:52224
	ds_read_b128 v[190:193], v175 offset:53248
	ds_read_b128 v[194:197], v175 offset:54272
	ds_read_b128 v[198:201], v175 offset:55296
	ds_read_b128 v[204:207], v175 offset:56320
	global_load_lds_dwordx4 v[224:225], off
	v_lshl_add_u64 v[224:225], v[230:231], 0, s[16:17]
	s_mov_b32 m0, s36
	s_nop 0
	global_load_lds_dwordx4 v[224:225], off
	s_barrier
; #define G_STAGE(bufoff, gbase, voff) do { _Pragma("unroll") for (int _i = 0; _i < 2; ++_i) \
;         __builtin_amdgcn_global_load_lds((const unsigned*)((const char*)(gbase) + (voff)[_i]), (LAS unsigned*)(lds + (bufoff) + ldsw + _i * 8192), 16, 0, 0); } while (0)
; #define G_MMA(ai, bj, At, Bt_) do { __builtin_amdgcn_s_setprio(1); _Pragma("unroll") for (int m = 0; m < 4; ++m) _Pragma("unroll") for (int n = 0; n < 2; ++n) _Pragma("unroll") for (int k = 0; k < 2; ++k) \
;         acc[ai][bj][m][n] = __builtin_amdgcn_mfma_f32_16x16x32_bf16(Bt_[n][k], At[m][k], acc[ai][bj][m][n], 0, 0, 0); __builtin_amdgcn_s_setprio(0); } while (0)
; #define G_WAIT_V(n) asm volatile("s_waitcnt vmcnt(" #n ")" ::: "memory")
; #define G_WAIT_L(n) asm volatile("s_waitcnt lgkmcnt(" #n ")" ::: "memory")
; #define G_BAR __builtin_amdgcn_s_barrier()
; #define G_SCHED __builtin_amdgcn_sched_barrier(0)
; template <class Epi, bool PERMROWS = false>
; DI void gemm_phase(LAS unsigned char* lds, const bf16_t* A, int lda, const bf16_t* Bt, int K, const Sched& S, const Epi& E) {
;     ...
;             G_BAR; G_WAIT_L(0); G_MMA(1, 0, At, B0); G_BAR; G_SCHED;
;             G_STAGE(G_SB(1, 1), b3 + hstepB, voffB);
;             G_WAIT_V(6); G_BAR; G_MMA(1, 1, At, B1); G_BAR;
;         }
;         E(acc, cur, wr, wc, fr, fq);
;     DI void operator()(const f32x4 (&acc)[2][2][4][2], const Unit& u, int wr, int wc, int fr, int fq) const {
;     ...
;                     const int colg = u.pn * BM + bj * HALF + wc * 32;
;                     f32x4 v0 = acc[ai][bj][m][0], v1 = acc[ai][bj][m][1];
;                     const int c0 = colg + 4 * fq;
;                     if (colg >= INW) continue;
;                     if (colg >= C_NAV && colg < C_CQ) {
	s_waitcnt lgkmcnt(0)
	s_setprio 1
	s_waitcnt lgkmcnt(0)
	v_mfma_f32_16x16x32_bf16 v[60:63], v[150:153], v[166:169], v[60:63]
	v_mfma_f32_16x16x32_bf16 v[56:59], v[158:161], v[166:169], v[56:59]
	v_mfma_f32_16x16x32_bf16 v[44:47], v[150:153], v[182:185], v[44:47]
	v_mfma_f32_16x16x32_bf16 v[40:43], v[158:161], v[182:185], v[40:43]
	v_mfma_f32_16x16x32_bf16 v[28:31], v[150:153], v[190:193], v[28:31]
	v_mfma_f32_16x16x32_bf16 v[24:27], v[158:161], v[190:193], v[24:27]
	v_mfma_f32_16x16x32_bf16 v[12:15], v[150:153], v[198:201], v[12:15]
	v_mfma_f32_16x16x32_bf16 v[8:11], v[158:161], v[198:201], v[8:11]
	v_mfma_f32_16x16x32_bf16 v[60:63], v[154:157], v[178:181], v[60:63]
	v_mfma_f32_16x16x32_bf16 v[56:59], v[162:165], v[178:181], v[56:59]
	v_mfma_f32_16x16x32_bf16 v[44:47], v[154:157], v[186:189], v[44:47]
	v_mfma_f32_16x16x32_bf16 v[40:43], v[162:165], v[186:189], v[40:43]
	v_mfma_f32_16x16x32_bf16 v[28:31], v[154:157], v[194:197], v[28:31]
	v_mfma_f32_16x16x32_bf16 v[24:27], v[162:165], v[194:197], v[24:27]
	v_mfma_f32_16x16x32_bf16 v[12:15], v[154:157], v[204:207], v[12:15]
	v_mfma_f32_16x16x32_bf16 v[8:11], v[162:165], v[204:207], v[8:11]
	s_setprio 0
	s_barrier
	s_add_u32 s14, s14, 0x80080
	s_addc_u32 s15, s15, 0
	s_add_i32 s28, s28, s83
	v_lshl_add_u64 v[150:151], s[14:15], 0, v[128:129]
	s_mov_b32 m0, s28
	s_nop 0
	global_load_lds_dwordx4 v[150:151], off
	v_lshl_add_u64 v[150:151], s[14:15], 0, v[130:131]
	s_add_i32 m0, s28, 0x2000
	s_nop 0
	global_load_lds_dwordx4 v[150:151], off
	s_waitcnt vmcnt(6)
	s_barrier
	s_setprio 1
	v_mfma_f32_16x16x32_bf16 v[52:55], v[208:211], v[166:169], v[52:55]
	v_mfma_f32_16x16x32_bf16 v[48:51], v[216:219], v[166:169], v[48:51]
	v_mfma_f32_16x16x32_bf16 v[36:39], v[208:211], v[182:185], v[36:39]
	v_mfma_f32_16x16x32_bf16 v[32:35], v[216:219], v[182:185], v[32:35]
	v_mfma_f32_16x16x32_bf16 v[20:23], v[208:211], v[190:193], v[20:23]
	v_mfma_f32_16x16x32_bf16 v[16:19], v[216:219], v[190:193], v[16:19]
	v_mfma_f32_16x16x32_bf16 v[4:7], v[208:211], v[198:201], v[4:7]
	v_mfma_f32_16x16x32_bf16 v[0:3], v[216:219], v[198:201], v[0:3]
	v_mfma_f32_16x16x32_bf16 v[52:55], v[212:215], v[178:181], v[52:55]
	v_mfma_f32_16x16x32_bf16 v[48:51], v[220:223], v[178:181], v[48:51]
	v_mfma_f32_16x16x32_bf16 v[36:39], v[212:215], v[186:189], v[36:39]
	v_mfma_f32_16x16x32_bf16 v[32:35], v[220:223], v[186:189], v[32:35]
	v_mfma_f32_16x16x32_bf16 v[20:23], v[212:215], v[194:197], v[20:23]
	v_mfma_f32_16x16x32_bf16 v[16:19], v[220:223], v[194:197], v[16:19]
	v_mfma_f32_16x16x32_bf16 v[4:7], v[212:215], v[204:207], v[4:7]
	v_mfma_f32_16x16x32_bf16 v[0:3], v[220:223], v[204:207], v[0:3]
	s_setprio 0
	s_add_i32 s43, s43, 2
	s_add_u32 s27, s27, 0x100
	s_addc_u32 s42, s42, 0
	s_add_u32 s12, s12, 0x100
	s_addc_u32 s13, s13, 0
	s_cmp_gt_u32 s43, 29
	s_barrier
	s_cbranch_scc0 .LBB0_1981
	v_bfe_u32 v194, v202, 6, 2
	v_and_b32_e32 v169, 15, v202
	v_readfirstlane_b32 s11, v194
	s_lshl_b32 s29, s0, 8
	s_lshl_b32 s54, s11, 5
	s_add_u32 s29, s29, s54
	s_mov_b32 s32, 1
	s_cmpk_lt_u32 s29, 0x600
	s_cbranch_scc1 .Lip1_c0_d
	s_mov_b32 s32, 4
	s_cmpk_lt_u32 s29, 0x900
	s_cbranch_scc1 .Lip1_c0_d
	s_mov_b32 s32, 6
	s_cmpk_lt_u32 s29, 0xd00
	s_cbranch_scc1 .Lip1_c0_d
	s_mov_b32 s32, 7
	s_cmpk_lt_u32 s29, 0xd40
	s_cbranch_scc1 .Lip1_c0_d
	s_mov_b32 s32, 2
	s_cmpk_lt_u32 s29, 0xfc0
	s_cbranch_scc1 .Lip1_c0_d
	s_mov_b32 s32, 3
	s_cmpk_lt_u32 s29, 0x1240
	s_cbranch_scc1 .Lip1_c0_d
	s_mov_b32 s32, 5
	s_cmpk_lt_u32 s29, 0x14c0
	s_cbranch_scc1 .Lip1_c0_d
	s_mov_b32 s32, 1
	s_cmpk_lt_u32 s29, 0x1740
	s_cbranch_scc1 .Lip1_c0_d
	s_mov_b32 s32, 0
.Lip1_c0_d:
	s_add_u32 s29, s29, 0x80
	s_mov_b32 s43, 1
	s_cmpk_lt_u32 s29, 0x600
	s_cbranch_scc1 .Lip1_c1_d
	s_mov_b32 s43, 4
	s_cmpk_lt_u32 s29, 0x900
	s_cbranch_scc1 .Lip1_c1_d
	s_mov_b32 s43, 6
	s_cmpk_lt_u32 s29, 0xd00
	s_cbranch_scc1 .Lip1_c1_d
	s_mov_b32 s43, 7
	s_cmpk_lt_u32 s29, 0xd40
	s_cbranch_scc1 .Lip1_c1_d
	s_mov_b32 s43, 2
	s_cmpk_lt_u32 s29, 0xfc0
	s_cbranch_scc1 .Lip1_c1_d
	s_mov_b32 s43, 3
	s_cmpk_lt_u32 s29, 0x1240
	s_cbranch_scc1 .Lip1_c1_d
	s_mov_b32 s43, 5
	s_cmpk_lt_u32 s29, 0x14c0
	s_cbranch_scc1 .Lip1_c1_d
	s_mov_b32 s43, 1
	s_cmpk_lt_u32 s29, 0x1740
	s_cbranch_scc1 .Lip1_c1_d
	s_mov_b32 s43, 0
; DI void st_bf16x4(bf16_t* p, f32x4 v) { u32x2 w; w.x = cvt_pk_bf16(v[0], v[1]); w.y = cvt_pk_bf16(v[2], v[3]); *(u32x2*)p = w; }
;     DI void operator()(const f32x4 (&acc)[2][2][4][2], const Unit& u, int wr, int wc, int fr, int fq) const {
;         bf16_t* P = (bf16_t*)(ws + WS_P);
;         const int b = u.pm / 9;
; #pragma unroll
;         for (int ai = 0; ai < 2; ++ai)
; #pragma unroll
;             for (int m = 0; m < 4; ++m) {
;                 const int row = u.pm * BM + ai * HALF + wr * 64 + m * 16 + fr;
;                 const int r = row - b * RB; const bool lat = r >= CL; const int t = r - CL;
; #pragma unroll
;                 for (int bj = 0; bj < 2; ++bj) {
;                     const int colg = u.pn * BM + bj * HALF + wc * 32;
;                     f32x4 v0 = acc[ai][bj][m][0], v1 = acc[ai][bj][m][1];
;                     const int c0 = colg + 4 * fq;
;                     if (colg >= INW) continue;
;                     if (colg >= C_NAV && colg < C_CQ) {
;                         st_tr16x32(spare + (wr * 4 + wc) * 1024, (bf16_t*)(ws + WS_VTNA) + ((size_t)b * 768 + (colg - C_NAV)) * RB + (r - fr), v0, v1, fr, fq, fq * 16 + fr);
;                     } else if (colg >= C_RV && colg < C_RG) {
;                         st_tr16x32(spare + (wr * 4 + wc) * 1024, (bf16_t*)(ws + WS_VTR) + ((size_t)b * 640 + (colg - C_RV)) * RB + (r - fr), v0, v1, fr, fq, fq * 16 + fr);
;                     } else if (colg >= C_KPE && colg < C_RQ) {
;                         if (lat) rope4(v0, v1, (const float*)(ws + WS_TABM) + ((size_t)t * 32 + ((colg - C_KPE) >> 5) * 16 + 4 * fq) * 2);
;                         bf16_t* kp = (bf16_t*)(ws + WS_KPE) + (size_t)row * 64 + (c0 - C_KPE);
;                         st_bf16x4(kp, v0); st_bf16x4(kp + 16, v1);
;                     } else if (colg >= C_RQ && colg < C_RV) {
;                         if (lat) rope4(v0, v1, (const float*)(ws + WS_TABR) + ((size_t)t * 64 + (((colg - C_RQ) & 127) >> 5) * 16 + 4 * fq) * 2);
.Lip1_c1_d:
	s_sub_u32 s29, s29, 0x80
	v_bfe_u32 v194, v202, 8, 1
	v_lshl_add_u32 v195, v194, 6, v169
	v_bfe_u32 v196, v202, 4, 2
	v_and_b32_e32 v197, 63, v202
	s_mul_i32 s27, s10, 57
	s_lshr_b32 s27, s27, 9
	s_mul_i32 s54, s27, 9
	s_sub_u32 s22, s10, s54
	v_mul_u32_u24_e32 v169, 0x3000, v195
	v_lshl_add_u32 v150, v196, 3, v169
	v_add_u32_e32 v151, 0x30000, v150
	v_add_u32_e32 v152, 0x60000, v150
	v_add_u32_e32 v153, 0x90000, v150
	v_add_u32_e32 v154, 0x180000, v150
	v_add_u32_e32 v155, 0x1b0000, v150
	v_add_u32_e32 v156, 0x1e0000, v150
	v_add_u32_e32 v157, 0x210000, v150
	v_lshrrev_b32_e32 v169, 6, v202
	v_lshlrev_b32_e32 v169, 10, v169
	v_add_u32_e32 v169, 0x20000, v169
	v_and_b32_e32 v194, 15, v202
	v_lshl_add_u32 v167, v196, 7, v169
	v_lshl_add_u32 v167, v194, 1, v167
	v_lshrrev_b32_e32 v194, 1, v197
	v_lshl_add_u32 v168, v194, 5, v169
	v_and_b32_e32 v169, 1, v197
	v_lshl_add_u32 v168, v169, 4, v168
	v_mul_u32_u24_e32 v166, 0x1200, v194
	v_lshl_add_u32 v166, v169, 4, v166
	v_bfe_u32 v169, v202, 8, 1
	v_lshl_add_u32 v166, v169, 7, v166
	s_cmp_eq_u32 s32, 0
	s_cbranch_scc1 .Lip1_k0_end
	s_cmp_eq_u32 s32, 1
	s_cbranch_scc1 .Lip1_k0_plain
	s_cmp_eq_u32 s32, 4
	s_cbranch_scc1 .Lip1_k0_nav
	s_cmp_eq_u32 s32, 5
	s_cbranch_scc1 .Lip1_k0_rv
	s_cmp_eq_u32 s32, 6
	s_cbranch_scc1 .Lip1_k0_ssq
	s_cmp_eq_u32 s32, 7
	s_cbranch_scc1 .Lip1_k0_kpe
	s_cmp_eq_u32 s22, 0
	s_cbranch_scc1 .Lip1_nr0
	s_sub_u32 s69, s29, 0xd40
	s_and_b32 s69, s69, 0x7f
	s_lshr_b32 s69, s69, 5
	s_lshl_b32 s69, s69, 7
	s_sub_u32 s54, s22, 1
	s_lshl_b32 s54, s54, 17
	s_add_u32 s54, s54, s69
	v_lshlrev_b32_e32 v169, 5, v196
	v_lshl_add_u32 v158, v195, 9, v169
	v_add_u32_e32 v158, s54, v158
	v_add_u32_e32 v159, 0x2000, v158
	v_add_u32_e32 v160, 0x4000, v158
	v_add_u32_e32 v161, 0x6000, v158
	v_add_u32_e32 v162, 0x10000, v158
	v_add_u32_e32 v163, 0x12000, v158
	v_add_u32_e32 v164, 0x14000, v158
	v_add_u32_e32 v165, 0x16000, v158
	s_add_u32 s14, s50, 0x100000
	s_addc_u32 s15, s51, 0
	global_load_dwordx4 v[204:207], v158, s[14:15]
	global_load_dwordx4 v[208:211], v158, s[14:15] offset:16
	global_load_dwordx4 v[212:215], v159, s[14:15]
	global_load_dwordx4 v[216:219], v159, s[14:15] offset:16
	global_load_dwordx4 v[220:223], v160, s[14:15]
	global_load_dwordx4 v[224:227], v160, s[14:15] offset:16
	global_load_dwordx4 v[228:231], v161, s[14:15]
	global_load_dwordx4 v[232:235], v161, s[14:15] offset:16
	global_load_dwordx4 v[236:239], v162, s[14:15]
	global_load_dwordx4 v[240:243], v162, s[14:15] offset:16
	global_load_dwordx4 v[244:247], v163, s[14:15]
	global_load_dwordx4 v[248:251], v163, s[14:15] offset:16
	global_load_dwordx4 v[178:181], v164, s[14:15]
	global_load_dwordx4 v[182:185], v164, s[14:15] offset:16
	global_load_dwordx4 v[186:189], v165, s[14:15]
	global_load_dwordx4 v[190:193], v165, s[14:15] offset:16
	s_waitcnt vmcnt(0)
	v_mul_f32_e32 v169, v124, v205
	v_mul_f32_e32 v124, v124, v204
	v_fma_f32 v124, -v120, v205, v124
	v_fma_f32 v120, v120, v204, v169
	v_mul_f32_e32 v169, v125, v207
	v_mul_f32_e32 v125, v125, v206
	v_fma_f32 v125, -v121, v207, v125
	v_fma_f32 v121, v121, v206, v169
	v_mul_f32_e32 v169, v126, v209
	v_mul_f32_e32 v126, v126, v208
	v_fma_f32 v126, -v122, v209, v126
	v_fma_f32 v122, v122, v208, v169
	v_mul_f32_e32 v169, v127, v211
	v_mul_f32_e32 v127, v127, v210
	v_fma_f32 v127, -v123, v211, v127
	v_fma_f32 v123, v123, v210, v169
	v_mul_f32_e32 v169, v108, v213
	v_mul_f32_e32 v108, v108, v212
	v_fma_f32 v108, -v104, v213, v108
	v_fma_f32 v104, v104, v212, v169
	v_mul_f32_e32 v169, v109, v215
	v_mul_f32_e32 v109, v109, v214
	v_fma_f32 v109, -v105, v215, v109
	v_fma_f32 v105, v105, v214, v169
	v_mul_f32_e32 v169, v110, v217
	v_mul_f32_e32 v110, v110, v216
	v_fma_f32 v110, -v106, v217, v110
	v_fma_f32 v106, v106, v216, v169
	v_mul_f32_e32 v169, v111, v219
	v_mul_f32_e32 v111, v111, v218
	v_fma_f32 v111, -v107, v219, v111
	v_fma_f32 v107, v107, v218, v169
	v_mul_f32_e32 v169, v92, v221
	v_mul_f32_e32 v92, v92, v220
	v_fma_f32 v92, -v88, v221, v92
	v_fma_f32 v88, v88, v220, v169
	v_mul_f32_e32 v169, v93, v223
	v_mul_f32_e32 v93, v93, v222
	v_fma_f32 v93, -v89, v223, v93
	v_fma_f32 v89, v89, v222, v169
	v_mul_f32_e32 v169, v94, v225
	v_mul_f32_e32 v94, v94, v224
	v_fma_f32 v94, -v90, v225, v94
	v_fma_f32 v90, v90, v224, v169
	v_mul_f32_e32 v169, v95, v227
	v_mul_f32_e32 v95, v95, v226
	v_fma_f32 v95, -v91, v227, v95
	v_fma_f32 v91, v91, v226, v169
	v_mul_f32_e32 v169, v76, v229
	v_mul_f32_e32 v76, v76, v228
	v_fma_f32 v76, -v72, v229, v76
	v_fma_f32 v72, v72, v228, v169
	v_mul_f32_e32 v169, v77, v231
	v_mul_f32_e32 v77, v77, v230
	v_fma_f32 v77, -v73, v231, v77
	v_fma_f32 v73, v73, v230, v169
	v_mul_f32_e32 v169, v78, v233
	v_mul_f32_e32 v78, v78, v232
	v_fma_f32 v78, -v74, v233, v78
	v_fma_f32 v74, v74, v232, v169
	v_mul_f32_e32 v169, v79, v235
	v_mul_f32_e32 v79, v79, v234
	v_fma_f32 v79, -v75, v235, v79
	v_fma_f32 v75, v75, v234, v169
	v_mul_f32_e32 v169, v60, v237
	v_mul_f32_e32 v60, v60, v236
	v_fma_f32 v60, -v56, v237, v60
	v_fma_f32 v56, v56, v236, v169
	v_mul_f32_e32 v169, v61, v239
	v_mul_f32_e32 v61, v61, v238
	v_fma_f32 v61, -v57, v239, v61
	v_fma_f32 v57, v57, v238, v169
	v_mul_f32_e32 v169, v62, v241
	v_mul_f32_e32 v62, v62, v240
	v_fma_f32 v62, -v58, v241, v62
	v_fma_f32 v58, v58, v240, v169
	v_mul_f32_e32 v169, v63, v243
	v_mul_f32_e32 v63, v63, v242
	v_fma_f32 v63, -v59, v243, v63
	v_fma_f32 v59, v59, v242, v169
	v_mul_f32_e32 v169, v44, v245
	v_mul_f32_e32 v44, v44, v244
	v_fma_f32 v44, -v40, v245, v44
	v_fma_f32 v40, v40, v244, v169
	v_mul_f32_e32 v169, v45, v247
	v_mul_f32_e32 v45, v45, v246
	v_fma_f32 v45, -v41, v247, v45
	v_fma_f32 v41, v41, v246, v169
	v_mul_f32_e32 v169, v46, v249
	v_mul_f32_e32 v46, v46, v248
	v_fma_f32 v46, -v42, v249, v46
	v_fma_f32 v42, v42, v248, v169
	v_mul_f32_e32 v169, v47, v251
	v_mul_f32_e32 v47, v47, v250
	v_fma_f32 v47, -v43, v251, v47
	v_fma_f32 v43, v43, v250, v169
	v_mul_f32_e32 v169, v28, v179
	v_mul_f32_e32 v28, v28, v178
	v_fma_f32 v28, -v24, v179, v28
	v_fma_f32 v24, v24, v178, v169
	v_mul_f32_e32 v169, v29, v181
	v_mul_f32_e32 v29, v29, v180
	v_fma_f32 v29, -v25, v181, v29
	v_fma_f32 v25, v25, v180, v169
	v_mul_f32_e32 v169, v30, v183
	v_mul_f32_e32 v30, v30, v182
	v_fma_f32 v30, -v26, v183, v30
	v_fma_f32 v26, v26, v182, v169
	v_mul_f32_e32 v169, v31, v185
	v_mul_f32_e32 v31, v31, v184
	v_fma_f32 v31, -v27, v185, v31
	v_fma_f32 v27, v27, v184, v169
	v_mul_f32_e32 v169, v12, v187
	v_mul_f32_e32 v12, v12, v186
	v_fma_f32 v12, -v8, v187, v12
	v_fma_f32 v8, v8, v186, v169
	v_mul_f32_e32 v169, v13, v189
	v_mul_f32_e32 v13, v13, v188
	v_fma_f32 v13, -v9, v189, v13
	v_fma_f32 v9, v9, v188, v169
	v_mul_f32_e32 v169, v14, v191
	v_mul_f32_e32 v14, v14, v190
	v_fma_f32 v14, -v10, v191, v14
	v_fma_f32 v10, v10, v190, v169
	v_mul_f32_e32 v169, v15, v193
	v_mul_f32_e32 v15, v15, v192
	v_fma_f32 v15, -v11, v193, v15
	v_fma_f32 v11, v11, v192, v169

; DI void rope4(f32x4& v0, f32x4& v1, const float* tab  ) {
;     const f32x4 t0 = *(const f32x4*)tab, t1 = *(const f32x4*)(tab + 4);
;     const float c[4] = {t0[0], t0[2], t1[0], t1[2]}, s[4] = {t0[1], t0[3], t1[1], t1[3]};
; #pragma unroll
;     for (int j = 0; j < 4; ++j) { const float a = v0[j], b = v1[j]; v0[j] = a * c[j] - b * s[j]; v1[j] = b * c[j] + a * s[j]; }
; }
;     DI void operator()(const f32x4 (&acc)[2][2][4][2], const Unit& u, int wr, int wc, int fr, int fq) const {
;     ...
;                     } else if (colg >= C_KPE && colg < C_RQ) {
;                         if (lat) rope4(v0, v1, (const float*)(ws + WS_TABM) + ((size_t)t * 32 + ((colg - C_KPE) >> 5) * 16 + 4 * fq) * 2);
.Lip1_k0_kpe:
	s_cmp_eq_u32 s22, 0
	s_cbranch_scc1 .Lip1_nr0k
	s_sub_u32 s69, s29, 0xd00
	s_and_b32 s69, s69, 0x7f
	s_lshr_b32 s69, s69, 5
	s_lshl_b32 s69, s69, 7
	s_sub_u32 s54, s22, 1
	s_lshl_b32 s54, s54, 16
	s_add_u32 s54, s54, s69
	v_lshlrev_b32_e32 v169, 5, v196
	v_lshl_add_u32 v158, v195, 8, v169
	v_add_u32_e32 v158, s54, v158
	v_add_u32_e32 v159, 0x1000, v158
	v_add_u32_e32 v160, 0x2000, v158
	v_add_u32_e32 v161, 0x3000, v158
	v_add_u32_e32 v162, 0x8000, v158
	v_add_u32_e32 v163, 0x9000, v158
	v_add_u32_e32 v164, 0xa000, v158
	v_add_u32_e32 v165, 0xb000, v158
	s_add_u32 s14, s50, 0x80000
	s_addc_u32 s15, s51, 0
	global_load_dwordx4 v[204:207], v158, s[14:15]
	global_load_dwordx4 v[208:211], v158, s[14:15] offset:16
	global_load_dwordx4 v[212:215], v159, s[14:15]
	global_load_dwordx4 v[216:219], v159, s[14:15] offset:16
	global_load_dwordx4 v[220:223], v160, s[14:15]
	global_load_dwordx4 v[224:227], v160, s[14:15] offset:16
	global_load_dwordx4 v[228:231], v161, s[14:15]
	global_load_dwordx4 v[232:235], v161, s[14:15] offset:16
	global_load_dwordx4 v[236:239], v162, s[14:15]
	global_load_dwordx4 v[240:243], v162, s[14:15] offset:16
	global_load_dwordx4 v[244:247], v163, s[14:15]
	global_load_dwordx4 v[248:251], v163, s[14:15] offset:16
	global_load_dwordx4 v[178:181], v164, s[14:15]
	global_load_dwordx4 v[182:185], v164, s[14:15] offset:16
	global_load_dwordx4 v[186:189], v165, s[14:15]
	global_load_dwordx4 v[190:193], v165, s[14:15] offset:16
	s_waitcnt vmcnt(0)
	v_mul_f32_e32 v169, v124, v205
	v_mul_f32_e32 v124, v124, v204
	v_fma_f32 v124, -v120, v205, v124
	v_fma_f32 v120, v120, v204, v169
	v_mul_f32_e32 v169, v125, v207
	v_mul_f32_e32 v125, v125, v206
	v_fma_f32 v125, -v121, v207, v125
	v_fma_f32 v121, v121, v206, v169
	v_mul_f32_e32 v169, v126, v209
	v_mul_f32_e32 v126, v126, v208
	v_fma_f32 v126, -v122, v209, v126
	v_fma_f32 v122, v122, v208, v169
	v_mul_f32_e32 v169, v127, v211
	v_mul_f32_e32 v127, v127, v210
	v_fma_f32 v127, -v123, v211, v127
	v_fma_f32 v123, v123, v210, v169
	v_mul_f32_e32 v169, v108, v213
	v_mul_f32_e32 v108, v108, v212
	v_fma_f32 v108, -v104, v213, v108
	v_fma_f32 v104, v104, v212, v169
	v_mul_f32_e32 v169, v109, v215
	v_mul_f32_e32 v109, v109, v214
	v_fma_f32 v109, -v105, v215, v109
	v_fma_f32 v105, v105, v214, v169
	v_mul_f32_e32 v169, v110, v217
	v_mul_f32_e32 v110, v110, v216
	v_fma_f32 v110, -v106, v217, v110
	v_fma_f32 v106, v106, v216, v169
	v_mul_f32_e32 v169, v111, v219
	v_mul_f32_e32 v111, v111, v218
	v_fma_f32 v111, -v107, v219, v111
	v_fma_f32 v107, v107, v218, v169
	v_mul_f32_e32 v169, v92, v221
	v_mul_f32_e32 v92, v92, v220
	v_fma_f32 v92, -v88, v221, v92
	v_fma_f32 v88, v88, v220, v169
	v_mul_f32_e32 v169, v93, v223
	v_mul_f32_e32 v93, v93, v222
	v_fma_f32 v93, -v89, v223, v93
	v_fma_f32 v89, v89, v222, v169
	v_mul_f32_e32 v169, v94, v225
	v_mul_f32_e32 v94, v94, v224
	v_fma_f32 v94, -v90, v225, v94
	v_fma_f32 v90, v90, v224, v169
	v_mul_f32_e32 v169, v95, v227
	v_mul_f32_e32 v95, v95, v226
	v_fma_f32 v95, -v91, v227, v95
	v_fma_f32 v91, v91, v226, v169
	v_mul_f32_e32 v169, v76, v229
	v_mul_f32_e32 v76, v76, v228
	v_fma_f32 v76, -v72, v229, v76
	v_fma_f32 v72, v72, v228, v169
	v_mul_f32_e32 v169, v77, v231
	v_mul_f32_e32 v77, v77, v230
	v_fma_f32 v77, -v73, v231, v77
	v_fma_f32 v73, v73, v230, v169
	v_mul_f32_e32 v169, v78, v233
	v_mul_f32_e32 v78, v78, v232
	v_fma_f32 v78, -v74, v233, v78
	v_fma_f32 v74, v74, v232, v169
	v_mul_f32_e32 v169, v79, v235
	v_mul_f32_e32 v79, v79, v234
	v_fma_f32 v79, -v75, v235, v79
	v_fma_f32 v75, v75, v234, v169
	v_mul_f32_e32 v169, v60, v237
	v_mul_f32_e32 v60, v60, v236
	v_fma_f32 v60, -v56, v237, v60
	v_fma_f32 v56, v56, v236, v169
	v_mul_f32_e32 v169, v61, v239
	v_mul_f32_e32 v61, v61, v238
	v_fma_f32 v61, -v57, v239, v61
	v_fma_f32 v57, v57, v238, v169
	v_mul_f32_e32 v169, v62, v241
	v_mul_f32_e32 v62, v62, v240
	v_fma_f32 v62, -v58, v241, v62
	v_fma_f32 v58, v58, v240, v169
	v_mul_f32_e32 v169, v63, v243
	v_mul_f32_e32 v63, v63, v242
	v_fma_f32 v63, -v59, v243, v63
	v_fma_f32 v59, v59, v242, v169
	v_mul_f32_e32 v169, v44, v245
	v_mul_f32_e32 v44, v44, v244
	v_fma_f32 v44, -v40, v245, v44
	v_fma_f32 v40, v40, v244, v169
	v_mul_f32_e32 v169, v45, v247
	v_mul_f32_e32 v45, v45, v246
	v_fma_f32 v45, -v41, v247, v45
	v_fma_f32 v41, v41, v246, v169
	v_mul_f32_e32 v169, v46, v249
	v_mul_f32_e32 v46, v46, v248
	v_fma_f32 v46, -v42, v249, v46
	v_fma_f32 v42, v42, v248, v169
	v_mul_f32_e32 v169, v47, v251
	v_mul_f32_e32 v47, v47, v250
	v_fma_f32 v47, -v43, v251, v47
	v_fma_f32 v43, v43, v250, v169
	v_mul_f32_e32 v169, v28, v179
	v_mul_f32_e32 v28, v28, v178
	v_fma_f32 v28, -v24, v179, v28
	v_fma_f32 v24, v24, v178, v169
	v_mul_f32_e32 v169, v29, v181
	v_mul_f32_e32 v29, v29, v180
	v_fma_f32 v29, -v25, v181, v29
	v_fma_f32 v25, v25, v180, v169
	v_mul_f32_e32 v169, v30, v183
	v_mul_f32_e32 v30, v30, v182
	v_fma_f32 v30, -v26, v183, v30
	v_fma_f32 v26, v26, v182, v169
	v_mul_f32_e32 v169, v31, v185
	v_mul_f32_e32 v31, v31, v184
	v_fma_f32 v31, -v27, v185, v31
	v_fma_f32 v27, v27, v184, v169
	v_mul_f32_e32 v169, v12, v187
	v_mul_f32_e32 v12, v12, v186
	v_fma_f32 v12, -v8, v187, v12
	v_fma_f32 v8, v8, v186, v169
	v_mul_f32_e32 v169, v13, v189
	v_mul_f32_e32 v13, v13, v188
	v_fma_f32 v13, -v9, v189, v13
	v_fma_f32 v9, v9, v188, v169
	v_mul_f32_e32 v169, v14, v191
	v_mul_f32_e32 v14, v14, v190
	v_fma_f32 v14, -v10, v191, v14
	v_fma_f32 v10, v10, v190, v169
	v_mul_f32_e32 v169, v15, v193
	v_mul_f32_e32 v15, v15, v192
	v_fma_f32 v15, -v11, v193, v15
	v_fma_f32 v11, v11, v192, v169
; DI void st_bf16x4(bf16_t* p, f32x4 v) { u32x2 w; w.x = cvt_pk_bf16(v[0], v[1]); w.y = cvt_pk_bf16(v[2], v[3]); *(u32x2*)p = w; }
;     DI void operator()(const f32x4 (&acc)[2][2][4][2], const Unit& u, int wr, int wc, int fr, int fq) const {
;     ...
;                     } else if (colg >= C_KPE && colg < C_RQ) {
;                         if (lat) rope4(v0, v1, (const float*)(ws + WS_TABM) + ((size_t)t * 32 + ((colg - C_KPE) >> 5) * 16 + 4 * fq) * 2);
;                         bf16_t* kp = (bf16_t*)(ws + WS_KPE) + (size_t)row * 64 + (c0 - C_KPE);
;                         st_bf16x4(kp, v0); st_bf16x4(kp + 16, v1);
.Lip1_nr0k:
	s_lshl_b32 s54, s10, 15
	s_add_u32 s14, s50, 0x1cb00000
	s_addc_u32 s15, s51, 0
	s_add_u32 s14, s14, s54
	s_addc_u32 s15, s15, 0
	s_sub_u32 s54, s29, 0xd00
	s_lshl_b32 s54, s54, 1
	s_add_u32 s14, s14, s54
	s_addc_u32 s15, s15, 0
	v_lshlrev_b32_e32 v158, 7, v195
	v_lshl_add_u32 v158, v196, 3, v158
	v_add_u32_e32 v159, 0x800, v158
	v_add_u32_e32 v160, 0x1000, v158
	v_add_u32_e32 v161, 0x1800, v158
	v_add_u32_e32 v162, 0x4000, v158
	v_add_u32_e32 v163, 0x4800, v158
	v_add_u32_e32 v164, 0x5000, v158
	v_add_u32_e32 v165, 0x5800, v158
	v_cvt_pk_bf16_f32 v124, v124, v125
	v_cvt_pk_bf16_f32 v125, v126, v127
	global_store_dwordx2 v158, v[124:125], s[14:15] offset:0
	v_cvt_pk_bf16_f32 v120, v120, v121
	v_cvt_pk_bf16_f32 v121, v122, v123
	global_store_dwordx2 v158, v[120:121], s[14:15] offset:32
	v_cvt_pk_bf16_f32 v108, v108, v109
	v_cvt_pk_bf16_f32 v109, v110, v111
	global_store_dwordx2 v159, v[108:109], s[14:15] offset:0
	v_cvt_pk_bf16_f32 v104, v104, v105
	v_cvt_pk_bf16_f32 v105, v106, v107
	global_store_dwordx2 v159, v[104:105], s[14:15] offset:32
	v_cvt_pk_bf16_f32 v92, v92, v93
	v_cvt_pk_bf16_f32 v93, v94, v95
	global_store_dwordx2 v160, v[92:93], s[14:15] offset:0
	v_cvt_pk_bf16_f32 v88, v88, v89
	v_cvt_pk_bf16_f32 v89, v90, v91
	global_store_dwordx2 v160, v[88:89], s[14:15] offset:32
	v_cvt_pk_bf16_f32 v76, v76, v77
	v_cvt_pk_bf16_f32 v77, v78, v79
	global_store_dwordx2 v161, v[76:77], s[14:15] offset:0
	v_cvt_pk_bf16_f32 v72, v72, v73
	v_cvt_pk_bf16_f32 v73, v74, v75
	global_store_dwordx2 v161, v[72:73], s[14:15] offset:32
	v_cvt_pk_bf16_f32 v60, v60, v61
	v_cvt_pk_bf16_f32 v61, v62, v63
	global_store_dwordx2 v162, v[60:61], s[14:15] offset:0
	v_cvt_pk_bf16_f32 v56, v56, v57
	v_cvt_pk_bf16_f32 v57, v58, v59
	global_store_dwordx2 v162, v[56:57], s[14:15] offset:32
	v_cvt_pk_bf16_f32 v44, v44, v45
	v_cvt_pk_bf16_f32 v45, v46, v47
	global_store_dwordx2 v163, v[44:45], s[14:15] offset:0
	v_cvt_pk_bf16_f32 v40, v40, v41
	v_cvt_pk_bf16_f32 v41, v42, v43
	global_store_dwordx2 v163, v[40:41], s[14:15] offset:32
	v_cvt_pk_bf16_f32 v28, v28, v29
	v_cvt_pk_bf16_f32 v29, v30, v31
	global_store_dwordx2 v164, v[28:29], s[14:15] offset:0
	v_cvt_pk_bf16_f32 v24, v24, v25
	v_cvt_pk_bf16_f32 v25, v26, v27
	global_store_dwordx2 v164, v[24:25], s[14:15] offset:32
	v_cvt_pk_bf16_f32 v12, v12, v13
	v_cvt_pk_bf16_f32 v13, v14, v15
	global_store_dwordx2 v165, v[12:13], s[14:15] offset:0
	v_cvt_pk_bf16_f32 v8, v8, v9
	v_cvt_pk_bf16_f32 v9, v10, v11
	global_store_dwordx2 v165, v[8:9], s[14:15] offset:32
	s_branch .Lip1_k0_end
; DI void st_bf16x4(bf16_t* p, f32x4 v) { u32x2 w; w.x = cvt_pk_bf16(v[0], v[1]); w.y = cvt_pk_bf16(v[2], v[3]); *(u32x2*)p = w; }
; DI void rope4(f32x4& v0, f32x4& v1, const float* tab  ) {
;     const f32x4 t0 = *(const f32x4*)tab, t1 = *(const f32x4*)(tab + 4);
;     const float c[4] = {t0[0], t0[2], t1[0], t1[2]}, s[4] = {t0[1], t0[3], t1[1], t1[3]};
; #pragma unroll
;     for (int j = 0; j < 4; ++j) { const float a = v0[j], b = v1[j]; v0[j] = a * c[j] - b * s[j]; v1[j] = b * c[j] + a * s[j]; }
; }
;     DI void operator()(const f32x4 (&acc)[2][2][4][2], const Unit& u, int wr, int wc, int fr, int fq) const {
;     ...
;                     if (colg >= INW) continue;
;                     if (colg >= C_NAV && colg < C_CQ) {
;                         st_tr16x32(spare + (wr * 4 + wc) * 1024, (bf16_t*)(ws + WS_VTNA) + ((size_t)b * 768 + (colg - C_NAV)) * RB + (r - fr), v0, v1, fr, fq, fq * 16 + fr);
;                     } else if (colg >= C_RV && colg < C_RG) {
;                         st_tr16x32(spare + (wr * 4 + wc) * 1024, (bf16_t*)(ws + WS_VTR) + ((size_t)b * 640 + (colg - C_RV)) * RB + (r - fr), v0, v1, fr, fq, fq * 16 + fr);
;                     } else if (colg >= C_KPE && colg < C_RQ) {
;                         if (lat) rope4(v0, v1, (const float*)(ws + WS_TABM) + ((size_t)t * 32 + ((colg - C_KPE) >> 5) * 16 + 4 * fq) * 2);
;                         bf16_t* kp = (bf16_t*)(ws + WS_KPE) + (size_t)row * 64 + (c0 - C_KPE);
;                         st_bf16x4(kp, v0); st_bf16x4(kp + 16, v1);
;                     } else if (colg >= C_RQ && colg < C_RV) {
;                         if (lat) rope4(v0, v1, (const float*)(ws + WS_TABR) + ((size_t)t * 64 + (((colg - C_RQ) & 127) >> 5) * 16 + 4 * fq) * 2);
;                         if (colg >= C_RK) {
;                             v0 *= 0.08838834764831845f; v1 *= 0.08838834764831845f;
;                             st_tr16x32(spare + (wr * 4 + wc) * 1024, (bf16_t*)(ws + WS_KTR) + ((size_t)b * 640 + (colg - C_RK)) * RB + (r - fr), v0, v1, fr, fq, fq * 16 + fr);
;                         }
;                         st_bf16x4(P + (size_t)row * INP + c0, v0); st_bf16x4(P + (size_t)row * INP + c0 + 16, v1);
.Lip1_k0_end:
	s_add_u32 s29, s29, 0x80
	s_cmp_eq_u32 s43, 0
	s_cbranch_scc1 .Lip1_k1_end
	s_cmp_eq_u32 s43, 1
	s_cbranch_scc1 .Lip1_k1_plain
	s_cmp_eq_u32 s43, 4
	s_cbranch_scc1 .Lip1_k1_nav
	s_cmp_eq_u32 s43, 5
	s_cbranch_scc1 .Lip1_k1_rv
	s_cmp_eq_u32 s43, 6
	s_cbranch_scc1 .Lip1_k1_ssq
	s_cmp_eq_u32 s43, 7
	s_cbranch_scc1 .Lip1_k1_kpe
	s_cmp_eq_u32 s22, 0
	s_cbranch_scc1 .Lip1_nr1
	s_sub_u32 s69, s29, 0xd40
	s_and_b32 s69, s69, 0x7f
	s_lshr_b32 s69, s69, 5
	s_lshl_b32 s69, s69, 7
	s_sub_u32 s54, s22, 1
	s_lshl_b32 s54, s54, 17
	s_add_u32 s54, s54, s69
	v_lshlrev_b32_e32 v169, 5, v196
	v_lshl_add_u32 v158, v195, 9, v169
	v_add_u32_e32 v158, s54, v158
	v_add_u32_e32 v159, 0x2000, v158
	v_add_u32_e32 v160, 0x4000, v158
	v_add_u32_e32 v161, 0x6000, v158
	v_add_u32_e32 v162, 0x10000, v158
	v_add_u32_e32 v163, 0x12000, v158
	v_add_u32_e32 v164, 0x14000, v158
	v_add_u32_e32 v165, 0x16000, v158
	s_add_u32 s14, s50, 0x100000
	s_addc_u32 s15, s51, 0
	global_load_dwordx4 v[204:207], v158, s[14:15]
	global_load_dwordx4 v[208:211], v158, s[14:15] offset:16
	global_load_dwordx4 v[212:215], v159, s[14:15]
	global_load_dwordx4 v[216:219], v159, s[14:15] offset:16
	global_load_dwordx4 v[220:223], v160, s[14:15]
	global_load_dwordx4 v[224:227], v160, s[14:15] offset:16
	global_load_dwordx4 v[228:231], v161, s[14:15]
	global_load_dwordx4 v[232:235], v161, s[14:15] offset:16
	global_load_dwordx4 v[236:239], v162, s[14:15]
	global_load_dwordx4 v[240:243], v162, s[14:15] offset:16
	global_load_dwordx4 v[244:247], v163, s[14:15]
	global_load_dwordx4 v[248:251], v163, s[14:15] offset:16
	global_load_dwordx4 v[178:181], v164, s[14:15]
	global_load_dwordx4 v[182:185], v164, s[14:15] offset:16
	global_load_dwordx4 v[186:189], v165, s[14:15]
	global_load_dwordx4 v[190:193], v165, s[14:15] offset:16
	s_waitcnt vmcnt(0)
	v_mul_f32_e32 v169, v116, v205
	v_mul_f32_e32 v116, v116, v204
	v_fma_f32 v116, -v112, v205, v116
	v_fma_f32 v112, v112, v204, v169
	v_mul_f32_e32 v169, v117, v207
	v_mul_f32_e32 v117, v117, v206
	v_fma_f32 v117, -v113, v207, v117
	v_fma_f32 v113, v113, v206, v169
	v_mul_f32_e32 v169, v118, v209
	v_mul_f32_e32 v118, v118, v208
	v_fma_f32 v118, -v114, v209, v118
	v_fma_f32 v114, v114, v208, v169
	v_mul_f32_e32 v169, v119, v211
	v_mul_f32_e32 v119, v119, v210
	v_fma_f32 v119, -v115, v211, v119
	v_fma_f32 v115, v115, v210, v169
	v_mul_f32_e32 v169, v100, v213
	v_mul_f32_e32 v100, v100, v212
	v_fma_f32 v100, -v96, v213, v100
	v_fma_f32 v96, v96, v212, v169
	v_mul_f32_e32 v169, v101, v215
	v_mul_f32_e32 v101, v101, v214
	v_fma_f32 v101, -v97, v215, v101
	v_fma_f32 v97, v97, v214, v169
	v_mul_f32_e32 v169, v102, v217
	v_mul_f32_e32 v102, v102, v216
	v_fma_f32 v102, -v98, v217, v102
	v_fma_f32 v98, v98, v216, v169
	v_mul_f32_e32 v169, v103, v219
	v_mul_f32_e32 v103, v103, v218
	v_fma_f32 v103, -v99, v219, v103
	v_fma_f32 v99, v99, v218, v169
	v_mul_f32_e32 v169, v84, v221
	v_mul_f32_e32 v84, v84, v220
	v_fma_f32 v84, -v80, v221, v84
	v_fma_f32 v80, v80, v220, v169
	v_mul_f32_e32 v169, v85, v223
	v_mul_f32_e32 v85, v85, v222
	v_fma_f32 v85, -v81, v223, v85
	v_fma_f32 v81, v81, v222, v169
	v_mul_f32_e32 v169, v86, v225
	v_mul_f32_e32 v86, v86, v224
	v_fma_f32 v86, -v82, v225, v86
	v_fma_f32 v82, v82, v224, v169
	v_mul_f32_e32 v169, v87, v227
	v_mul_f32_e32 v87, v87, v226
	v_fma_f32 v87, -v83, v227, v87
	v_fma_f32 v83, v83, v226, v169
	v_mul_f32_e32 v169, v68, v229
	v_mul_f32_e32 v68, v68, v228
	v_fma_f32 v68, -v64, v229, v68
	v_fma_f32 v64, v64, v228, v169
	v_mul_f32_e32 v169, v69, v231
	v_mul_f32_e32 v69, v69, v230
	v_fma_f32 v69, -v65, v231, v69
	v_fma_f32 v65, v65, v230, v169
	v_mul_f32_e32 v169, v70, v233
	v_mul_f32_e32 v70, v70, v232
	v_fma_f32 v70, -v66, v233, v70
	v_fma_f32 v66, v66, v232, v169
	v_mul_f32_e32 v169, v71, v235
	v_mul_f32_e32 v71, v71, v234
	v_fma_f32 v71, -v67, v235, v71
	v_fma_f32 v67, v67, v234, v169
	v_mul_f32_e32 v169, v52, v237
	v_mul_f32_e32 v52, v52, v236
	v_fma_f32 v52, -v48, v237, v52
	v_fma_f32 v48, v48, v236, v169
	v_mul_f32_e32 v169, v53, v239
	v_mul_f32_e32 v53, v53, v238
	v_fma_f32 v53, -v49, v239, v53
	v_fma_f32 v49, v49, v238, v169
	v_mul_f32_e32 v169, v54, v241
	v_mul_f32_e32 v54, v54, v240
	v_fma_f32 v54, -v50, v241, v54
	v_fma_f32 v50, v50, v240, v169
	v_mul_f32_e32 v169, v55, v243
	v_mul_f32_e32 v55, v55, v242
	v_fma_f32 v55, -v51, v243, v55
	v_fma_f32 v51, v51, v242, v169
	v_mul_f32_e32 v169, v36, v245
	v_mul_f32_e32 v36, v36, v244
	v_fma_f32 v36, -v32, v245, v36
	v_fma_f32 v32, v32, v244, v169
	v_mul_f32_e32 v169, v37, v247
	v_mul_f32_e32 v37, v37, v246
	v_fma_f32 v37, -v33, v247, v37
	v_fma_f32 v33, v33, v246, v169
	v_mul_f32_e32 v169, v38, v249
	v_mul_f32_e32 v38, v38, v248
	v_fma_f32 v38, -v34, v249, v38
	v_fma_f32 v34, v34, v248, v169
	v_mul_f32_e32 v169, v39, v251
	v_mul_f32_e32 v39, v39, v250
	v_fma_f32 v39, -v35, v251, v39
	v_fma_f32 v35, v35, v250, v169
	v_mul_f32_e32 v169, v20, v179
	v_mul_f32_e32 v20, v20, v178
	v_fma_f32 v20, -v16, v179, v20
	v_fma_f32 v16, v16, v178, v169
	v_mul_f32_e32 v169, v21, v181
	v_mul_f32_e32 v21, v21, v180
	v_fma_f32 v21, -v17, v181, v21
	v_fma_f32 v17, v17, v180, v169
	v_mul_f32_e32 v169, v22, v183
	v_mul_f32_e32 v22, v22, v182
	v_fma_f32 v22, -v18, v183, v22
	v_fma_f32 v18, v18, v182, v169
	v_mul_f32_e32 v169, v23, v185
	v_mul_f32_e32 v23, v23, v184
	v_fma_f32 v23, -v19, v185, v23
	v_fma_f32 v19, v19, v184, v169
	v_mul_f32_e32 v169, v4, v187
	v_mul_f32_e32 v4, v4, v186
	v_fma_f32 v4, -v0, v187, v4
	v_fma_f32 v0, v0, v186, v169
	v_mul_f32_e32 v169, v5, v189
	v_mul_f32_e32 v5, v5, v188
	v_fma_f32 v5, -v1, v189, v5
	v_fma_f32 v1, v1, v188, v169
	v_mul_f32_e32 v169, v6, v191
	v_mul_f32_e32 v6, v6, v190
	v_fma_f32 v6, -v2, v191, v6
	v_fma_f32 v2, v2, v190, v169
	v_mul_f32_e32 v169, v7, v193
	v_mul_f32_e32 v7, v7, v192
	v_fma_f32 v7, -v3, v193, v7
	v_fma_f32 v3, v3, v192, v169

; DI void st_bf16x4(bf16_t* p, f32x4 v) { u32x2 w; w.x = cvt_pk_bf16(v[0], v[1]); w.y = cvt_pk_bf16(v[2], v[3]); *(u32x2*)p = w; }
; DI void rope4(f32x4& v0, f32x4& v1, const float* tab  ) {
;     const f32x4 t0 = *(const f32x4*)tab, t1 = *(const f32x4*)(tab + 4);
;     const float c[4] = {t0[0], t0[2], t1[0], t1[2]}, s[4] = {t0[1], t0[3], t1[1], t1[3]};
; #pragma unroll
;     for (int j = 0; j < 4; ++j) { const float a = v0[j], b = v1[j]; v0[j] = a * c[j] - b * s[j]; v1[j] = b * c[j] + a * s[j]; }
; }
;     DI void operator()(const f32x4 (&acc)[2][2][4][2], const Unit& u, int wr, int wc, int fr, int fq) const {
;     ...
;                     } else if (colg >= C_KPE && colg < C_RQ) {
;                         if (lat) rope4(v0, v1, (const float*)(ws + WS_TABM) + ((size_t)t * 32 + ((colg - C_KPE) >> 5) * 16 + 4 * fq) * 2);
;                         bf16_t* kp = (bf16_t*)(ws + WS_KPE) + (size_t)row * 64 + (c0 - C_KPE);
;                         st_bf16x4(kp, v0); st_bf16x4(kp + 16, v1);
.Lip1_k1_kpe:
	s_cmp_eq_u32 s22, 0
	s_cbranch_scc1 .Lip1_nr1k
	s_sub_u32 s69, s29, 0xd00
	s_and_b32 s69, s69, 0x7f
	s_lshr_b32 s69, s69, 5
	s_lshl_b32 s69, s69, 7
	s_sub_u32 s54, s22, 1
	s_lshl_b32 s54, s54, 16
	s_add_u32 s54, s54, s69
	v_lshlrev_b32_e32 v169, 5, v196
	v_lshl_add_u32 v158, v195, 8, v169
	v_add_u32_e32 v158, s54, v158
	v_add_u32_e32 v159, 0x1000, v158
	v_add_u32_e32 v160, 0x2000, v158
	v_add_u32_e32 v161, 0x3000, v158
	v_add_u32_e32 v162, 0x8000, v158
	v_add_u32_e32 v163, 0x9000, v158
	v_add_u32_e32 v164, 0xa000, v158
	v_add_u32_e32 v165, 0xb000, v158
	s_add_u32 s14, s50, 0x80000
	s_addc_u32 s15, s51, 0
	global_load_dwordx4 v[204:207], v158, s[14:15]
	global_load_dwordx4 v[208:211], v158, s[14:15] offset:16
	global_load_dwordx4 v[212:215], v159, s[14:15]
	global_load_dwordx4 v[216:219], v159, s[14:15] offset:16
	global_load_dwordx4 v[220:223], v160, s[14:15]
	global_load_dwordx4 v[224:227], v160, s[14:15] offset:16
	global_load_dwordx4 v[228:231], v161, s[14:15]
	global_load_dwordx4 v[232:235], v161, s[14:15] offset:16
	global_load_dwordx4 v[236:239], v162, s[14:15]
	global_load_dwordx4 v[240:243], v162, s[14:15] offset:16
	global_load_dwordx4 v[244:247], v163, s[14:15]
	global_load_dwordx4 v[248:251], v163, s[14:15] offset:16
	global_load_dwordx4 v[178:181], v164, s[14:15]
	global_load_dwordx4 v[182:185], v164, s[14:15] offset:16
	global_load_dwordx4 v[186:189], v165, s[14:15]
	global_load_dwordx4 v[190:193], v165, s[14:15] offset:16
	s_waitcnt vmcnt(0)
	v_mul_f32_e32 v169, v116, v205
	v_mul_f32_e32 v116, v116, v204
	v_fma_f32 v116, -v112, v205, v116
	v_fma_f32 v112, v112, v204, v169
	v_mul_f32_e32 v169, v117, v207
	v_mul_f32_e32 v117, v117, v206
	v_fma_f32 v117, -v113, v207, v117
	v_fma_f32 v113, v113, v206, v169
	v_mul_f32_e32 v169, v118, v209
	v_mul_f32_e32 v118, v118, v208
	v_fma_f32 v118, -v114, v209, v118
	v_fma_f32 v114, v114, v208, v169
	v_mul_f32_e32 v169, v119, v211
	v_mul_f32_e32 v119, v119, v210
	v_fma_f32 v119, -v115, v211, v119
	v_fma_f32 v115, v115, v210, v169
	v_mul_f32_e32 v169, v100, v213
	v_mul_f32_e32 v100, v100, v212
	v_fma_f32 v100, -v96, v213, v100
	v_fma_f32 v96, v96, v212, v169
	v_mul_f32_e32 v169, v101, v215
	v_mul_f32_e32 v101, v101, v214
	v_fma_f32 v101, -v97, v215, v101
	v_fma_f32 v97, v97, v214, v169
	v_mul_f32_e32 v169, v102, v217
	v_mul_f32_e32 v102, v102, v216
	v_fma_f32 v102, -v98, v217, v102
	v_fma_f32 v98, v98, v216, v169
	v_mul_f32_e32 v169, v103, v219
	v_mul_f32_e32 v103, v103, v218
	v_fma_f32 v103, -v99, v219, v103
	v_fma_f32 v99, v99, v218, v169
	v_mul_f32_e32 v169, v84, v221
	v_mul_f32_e32 v84, v84, v220
	v_fma_f32 v84, -v80, v221, v84
	v_fma_f32 v80, v80, v220, v169
	v_mul_f32_e32 v169, v85, v223
	v_mul_f32_e32 v85, v85, v222
	v_fma_f32 v85, -v81, v223, v85
	v_fma_f32 v81, v81, v222, v169
	v_mul_f32_e32 v169, v86, v225
	v_mul_f32_e32 v86, v86, v224
	v_fma_f32 v86, -v82, v225, v86
	v_fma_f32 v82, v82, v224, v169
	v_mul_f32_e32 v169, v87, v227
	v_mul_f32_e32 v87, v87, v226
	v_fma_f32 v87, -v83, v227, v87
	v_fma_f32 v83, v83, v226, v169
	v_mul_f32_e32 v169, v68, v229
	v_mul_f32_e32 v68, v68, v228
	v_fma_f32 v68, -v64, v229, v68
	v_fma_f32 v64, v64, v228, v169
	v_mul_f32_e32 v169, v69, v231
	v_mul_f32_e32 v69, v69, v230
	v_fma_f32 v69, -v65, v231, v69
	v_fma_f32 v65, v65, v230, v169
	v_mul_f32_e32 v169, v70, v233
	v_mul_f32_e32 v70, v70, v232
	v_fma_f32 v70, -v66, v233, v70
	v_fma_f32 v66, v66, v232, v169
	v_mul_f32_e32 v169, v71, v235
	v_mul_f32_e32 v71, v71, v234
	v_fma_f32 v71, -v67, v235, v71
	v_fma_f32 v67, v67, v234, v169
	v_mul_f32_e32 v169, v52, v237
	v_mul_f32_e32 v52, v52, v236
	v_fma_f32 v52, -v48, v237, v52
	v_fma_f32 v48, v48, v236, v169
	v_mul_f32_e32 v169, v53, v239
	v_mul_f32_e32 v53, v53, v238
	v_fma_f32 v53, -v49, v239, v53
	v_fma_f32 v49, v49, v238, v169
	v_mul_f32_e32 v169, v54, v241
	v_mul_f32_e32 v54, v54, v240
	v_fma_f32 v54, -v50, v241, v54
	v_fma_f32 v50, v50, v240, v169
	v_mul_f32_e32 v169, v55, v243
	v_mul_f32_e32 v55, v55, v242
	v_fma_f32 v55, -v51, v243, v55
	v_fma_f32 v51, v51, v242, v169
	v_mul_f32_e32 v169, v36, v245
	v_mul_f32_e32 v36, v36, v244
	v_fma_f32 v36, -v32, v245, v36
	v_fma_f32 v32, v32, v244, v169
	v_mul_f32_e32 v169, v37, v247
	v_mul_f32_e32 v37, v37, v246
	v_fma_f32 v37, -v33, v247, v37
	v_fma_f32 v33, v33, v246, v169
	v_mul_f32_e32 v169, v38, v249
	v_mul_f32_e32 v38, v38, v248
	v_fma_f32 v38, -v34, v249, v38
	v_fma_f32 v34, v34, v248, v169
	v_mul_f32_e32 v169, v39, v251
	v_mul_f32_e32 v39, v39, v250
	v_fma_f32 v39, -v35, v251, v39
	v_fma_f32 v35, v35, v250, v169
	v_mul_f32_e32 v169, v20, v179
	v_mul_f32_e32 v20, v20, v178
	v_fma_f32 v20, -v16, v179, v20
	v_fma_f32 v16, v16, v178, v169
	v_mul_f32_e32 v169, v21, v181
	v_mul_f32_e32 v21, v21, v180
	v_fma_f32 v21, -v17, v181, v21
	v_fma_f32 v17, v17, v180, v169
	v_mul_f32_e32 v169, v22, v183
	v_mul_f32_e32 v22, v22, v182
	v_fma_f32 v22, -v18, v183, v22
	v_fma_f32 v18, v18, v182, v169
	v_mul_f32_e32 v169, v23, v185
	v_mul_f32_e32 v23, v23, v184
	v_fma_f32 v23, -v19, v185, v23
	v_fma_f32 v19, v19, v184, v169
	v_mul_f32_e32 v169, v4, v187
	v_mul_f32_e32 v4, v4, v186
	v_fma_f32 v4, -v0, v187, v4
	v_fma_f32 v0, v0, v186, v169
	v_mul_f32_e32 v169, v5, v189
	v_mul_f32_e32 v5, v5, v188
	v_fma_f32 v5, -v1, v189, v5
	v_fma_f32 v1, v1, v188, v169
	v_mul_f32_e32 v169, v6, v191
	v_mul_f32_e32 v6, v6, v190
	v_fma_f32 v6, -v2, v191, v6
	v_fma_f32 v2, v2, v190, v169
	v_mul_f32_e32 v169, v7, v193
	v_mul_f32_e32 v7, v7, v192
	v_fma_f32 v7, -v3, v193, v7
	v_fma_f32 v3, v3, v192, v169
; DI unsigned cvt_pk_bf16(float lo, float hi) { unsigned r; asm volatile("v_cvt_pk_bf16_f32 %0, %1, %2" : "=v"(r) : "v"(lo), "v"(hi)); return r; }
; DI void st_bf16x4(bf16_t* p, f32x4 v) { u32x2 w; w.x = cvt_pk_bf16(v[0], v[1]); w.y = cvt_pk_bf16(v[2], v[3]); *(u32x2*)p = w; }
;     DI void operator()(const f32x4 (&acc)[2][2][4][2], const Unit& u, int wr, int wc, int fr, int fq) const {
;     ...
;                         bf16_t* kp = (bf16_t*)(ws + WS_KPE) + (size_t)row * 64 + (c0 - C_KPE);
;                         st_bf16x4(kp, v0); st_bf16x4(kp + 16, v1);
.Lip1_nr1k:
	s_lshl_b32 s54, s10, 15
	s_add_u32 s14, s50, 0x1cb00000
	s_addc_u32 s15, s51, 0
	s_add_u32 s14, s14, s54
	s_addc_u32 s15, s15, 0
	s_sub_u32 s54, s29, 0xd00
	s_lshl_b32 s54, s54, 1
	s_add_u32 s14, s14, s54
	s_addc_u32 s15, s15, 0
	v_lshlrev_b32_e32 v158, 7, v195
	v_lshl_add_u32 v158, v196, 3, v158
	v_add_u32_e32 v159, 0x800, v158
	v_add_u32_e32 v160, 0x1000, v158
	v_add_u32_e32 v161, 0x1800, v158
	v_add_u32_e32 v162, 0x4000, v158
	v_add_u32_e32 v163, 0x4800, v158
	v_add_u32_e32 v164, 0x5000, v158
	v_add_u32_e32 v165, 0x5800, v158
	v_cvt_pk_bf16_f32 v116, v116, v117
	v_cvt_pk_bf16_f32 v117, v118, v119
	global_store_dwordx2 v158, v[116:117], s[14:15] offset:0
	v_cvt_pk_bf16_f32 v112, v112, v113
	v_cvt_pk_bf16_f32 v113, v114, v115
	global_store_dwordx2 v158, v[112:113], s[14:15] offset:32
	v_cvt_pk_bf16_f32 v100, v100, v101
	v_cvt_pk_bf16_f32 v101, v102, v103
	global_store_dwordx2 v159, v[100:101], s[14:15] offset:0
	v_cvt_pk_bf16_f32 v96, v96, v97
	v_cvt_pk_bf16_f32 v97, v98, v99
	global_store_dwordx2 v159, v[96:97], s[14:15] offset:32
	v_cvt_pk_bf16_f32 v84, v84, v85
	v_cvt_pk_bf16_f32 v85, v86, v87
	global_store_dwordx2 v160, v[84:85], s[14:15] offset:0
	v_cvt_pk_bf16_f32 v80, v80, v81
	v_cvt_pk_bf16_f32 v81, v82, v83
	global_store_dwordx2 v160, v[80:81], s[14:15] offset:32
	v_cvt_pk_bf16_f32 v68, v68, v69
	v_cvt_pk_bf16_f32 v69, v70, v71
	global_store_dwordx2 v161, v[68:69], s[14:15] offset:0
	v_cvt_pk_bf16_f32 v64, v64, v65
	v_cvt_pk_bf16_f32 v65, v66, v67
	global_store_dwordx2 v161, v[64:65], s[14:15] offset:32
	v_cvt_pk_bf16_f32 v52, v52, v53
	v_cvt_pk_bf16_f32 v53, v54, v55
	global_store_dwordx2 v162, v[52:53], s[14:15] offset:0
	v_cvt_pk_bf16_f32 v48, v48, v49
	v_cvt_pk_bf16_f32 v49, v50, v51
	global_store_dwordx2 v162, v[48:49], s[14:15] offset:32
	v_cvt_pk_bf16_f32 v36, v36, v37
	v_cvt_pk_bf16_f32 v37, v38, v39
	global_store_dwordx2 v163, v[36:37], s[14:15] offset:0
	v_cvt_pk_bf16_f32 v32, v32, v33
	v_cvt_pk_bf16_f32 v33, v34, v35
	global_store_dwordx2 v163, v[32:33], s[14:15] offset:32
	v_cvt_pk_bf16_f32 v20, v20, v21
	v_cvt_pk_bf16_f32 v21, v22, v23
	global_store_dwordx2 v164, v[20:21], s[14:15] offset:0
	v_cvt_pk_bf16_f32 v16, v16, v17
	v_cvt_pk_bf16_f32 v17, v18, v19
	global_store_dwordx2 v164, v[16:17], s[14:15] offset:32
	v_cvt_pk_bf16_f32 v4, v4, v5
	v_cvt_pk_bf16_f32 v5, v6, v7
	global_store_dwordx2 v165, v[4:5], s[14:15] offset:0
	v_cvt_pk_bf16_f32 v0, v0, v1
	v_cvt_pk_bf16_f32 v1, v2, v3
	global_store_dwordx2 v165, v[0:1], s[14:15] offset:32
	s_branch .Lip1_k1_end
